# v44 + every 16-MFMA run in the six GEMM stream loops aligned to 8 bytes (s_nop pads in load sections, compensated after each loop)
# baseline (speedup 1.0000x reference)
.LBB0_185:
	ds_read_b128 v[148:151], v144
	ds_read_b128 v[152:155], v144 offset:1024
	ds_read_b128 v[156:159], v144 offset:2048
	ds_read_b128 v[160:163], v144 offset:3072
	ds_read_b128 v[164:167], v145
	ds_read_b128 v[168:171], v145 offset:1024
	ds_read_b128 v[172:175], v145 offset:2048
	ds_read_b128 v[176:179], v145 offset:3072
	s_add_u32 s20, s18, 0xfff80080
	s_addc_u32 s21, s19, -1
	s_cmp_eq_u32 s41, 28
	s_cselect_b32 s23, s11, s21
	s_cselect_b32 s22, s37, s20
	s_cselect_b32 s21, s13, s40
	s_cselect_b32 s20, s38, s39
	v_lshl_add_u64 v[180:181], s[18:19], 0, v[134:135]
	s_add_i32 m0, s3, 0xc000
	ds_read_b128 v[184:187], v146
	ds_read_b128 v[188:191], v146 offset:1024
	ds_read_b128 v[192:195], v146 offset:2048
	ds_read_b128 v[196:199], v146 offset:3072
	ds_read_b128 v[200:203], v146 offset:4096
	ds_read_b128 v[204:207], v146 offset:5120
	ds_read_b128 v[208:211], v146 offset:6144
	ds_read_b128 v[212:215], v146 offset:7168
	global_load_lds_dwordx4 v[180:181], off
	v_lshl_add_u64 v[180:181], s[18:19], 0, v[136:137]
	s_add_i32 m0, s3, 0xe000
	s_nop 0
	global_load_lds_dwordx4 v[180:181], off
	s_waitcnt vmcnt(8)
	s_waitcnt lgkmcnt(0)
	s_barrier
	s_setprio 1
	s_waitcnt lgkmcnt(0)
	v_mfma_f32_16x16x32_bf16 v[124:127], v[148:151], v[184:187], v[124:127]
	v_mfma_f32_16x16x32_bf16 v[120:123], v[156:159], v[184:187], v[120:123]
	v_mfma_f32_16x16x32_bf16 v[116:119], v[148:151], v[192:195], v[116:119]
	v_mfma_f32_16x16x32_bf16 v[112:115], v[156:159], v[192:195], v[112:115]
	v_mfma_f32_16x16x32_bf16 v[100:103], v[148:151], v[200:203], v[100:103]
	v_mfma_f32_16x16x32_bf16 v[96:99], v[156:159], v[200:203], v[96:99]
	v_mfma_f32_16x16x32_bf16 v[84:87], v[148:151], v[208:211], v[84:87]
	v_mfma_f32_16x16x32_bf16 v[80:83], v[156:159], v[208:211], v[80:83]
	v_mfma_f32_16x16x32_bf16 v[124:127], v[152:155], v[188:191], v[124:127]
	v_mfma_f32_16x16x32_bf16 v[120:123], v[160:163], v[188:191], v[120:123]
	v_mfma_f32_16x16x32_bf16 v[116:119], v[152:155], v[196:199], v[116:119]
	v_mfma_f32_16x16x32_bf16 v[112:115], v[160:163], v[196:199], v[112:115]
	v_mfma_f32_16x16x32_bf16 v[100:103], v[152:155], v[204:207], v[100:103]
	v_mfma_f32_16x16x32_bf16 v[96:99], v[160:163], v[204:207], v[96:99]
	v_mfma_f32_16x16x32_bf16 v[84:87], v[152:155], v[212:215], v[84:87]
	v_mfma_f32_16x16x32_bf16 v[80:83], v[160:163], v[212:215], v[80:83]
	s_setprio 0
	s_setprio 1
	v_mfma_f32_16x16x32_bf16 v[108:111], v[164:167], v[184:187], v[108:111]
	v_mfma_f32_16x16x32_bf16 v[104:107], v[172:175], v[184:187], v[104:107]
	v_mfma_f32_16x16x32_bf16 v[92:95], v[164:167], v[192:195], v[92:95]
	v_mfma_f32_16x16x32_bf16 v[88:91], v[172:175], v[192:195], v[88:91]
	v_mfma_f32_16x16x32_bf16 v[76:79], v[164:167], v[200:203], v[76:79]
	v_mfma_f32_16x16x32_bf16 v[72:75], v[172:175], v[200:203], v[72:75]
	v_mfma_f32_16x16x32_bf16 v[68:71], v[164:167], v[208:211], v[68:71]
	v_mfma_f32_16x16x32_bf16 v[64:67], v[172:175], v[208:211], v[64:67]
	v_mfma_f32_16x16x32_bf16 v[108:111], v[168:171], v[188:191], v[108:111]
	v_mfma_f32_16x16x32_bf16 v[104:107], v[176:179], v[188:191], v[104:107]
	v_mfma_f32_16x16x32_bf16 v[92:95], v[168:171], v[196:199], v[92:95]
	v_mfma_f32_16x16x32_bf16 v[88:91], v[176:179], v[196:199], v[88:91]
	v_mfma_f32_16x16x32_bf16 v[76:79], v[168:171], v[204:207], v[76:79]
	v_mfma_f32_16x16x32_bf16 v[72:75], v[176:179], v[204:207], v[72:75]
	v_mfma_f32_16x16x32_bf16 v[68:71], v[168:171], v[212:215], v[68:71]
	v_mfma_f32_16x16x32_bf16 v[64:67], v[176:179], v[212:215], v[64:67]
	s_setprio 0
	s_barrier
	s_add_i32 s42, s30, s2
	v_lshl_add_u64 v[180:181], s[20:21], 0, v[128:129]
	s_mov_b32 m0, s42
	ds_read_b128 v[184:187], v146 offset:16384
	ds_read_b128 v[188:191], v146 offset:17408
	ds_read_b128 v[192:195], v146 offset:18432
	ds_read_b128 v[196:199], v146 offset:19456
	ds_read_b128 v[200:203], v146 offset:20480
	ds_read_b128 v[204:207], v146 offset:21504
	ds_read_b128 v[208:211], v146 offset:22528
	ds_read_b128 v[212:215], v146 offset:23552
	global_load_lds_dwordx4 v[180:181], off
	s_add_i32 m0, s42, 0x2000
	s_add_u32 s42, s20, 0x80000
	v_lshl_add_u64 v[216:217], s[20:21], 0, v[130:131]
	s_addc_u32 s43, s21, 0
	s_add_i32 s48, s31, s2
	global_load_lds_dwordx4 v[216:217], off
	v_lshl_add_u64 v[218:219], s[42:43], 0, v[128:129]
	s_mov_b32 m0, s48
	v_lshl_add_u64 v[220:221], s[22:23], 0, v[130:131]
	global_load_lds_dwordx4 v[218:219], off
	v_lshl_add_u64 v[218:219], s[42:43], 0, v[130:131]
	s_add_i32 m0, s48, 0x2000
	s_nop 0
	global_load_lds_dwordx4 v[218:219], off
	v_lshl_add_u64 v[218:219], s[22:23], 0, v[128:129]
	s_mov_b32 m0, s3
	s_nop 0
	global_load_lds_dwordx4 v[218:219], off
	s_mov_b32 m0, s24
	s_nop 0
	global_load_lds_dwordx4 v[220:221], off
	s_nop 0
	s_waitcnt vmcnt(8)
	s_waitcnt lgkmcnt(0)
	s_barrier
	s_setprio 1
	s_waitcnt lgkmcnt(0)
	v_mfma_f32_16x16x32_bf16 v[60:63], v[148:151], v[184:187], v[60:63]
	v_mfma_f32_16x16x32_bf16 v[56:59], v[156:159], v[184:187], v[56:59]
	v_mfma_f32_16x16x32_bf16 v[52:55], v[148:151], v[192:195], v[52:55]
	v_mfma_f32_16x16x32_bf16 v[48:51], v[156:159], v[192:195], v[48:51]
	v_mfma_f32_16x16x32_bf16 v[36:39], v[148:151], v[200:203], v[36:39]
	v_mfma_f32_16x16x32_bf16 v[32:35], v[156:159], v[200:203], v[32:35]
	v_mfma_f32_16x16x32_bf16 v[20:23], v[148:151], v[208:211], v[20:23]
	v_mfma_f32_16x16x32_bf16 v[16:19], v[156:159], v[208:211], v[16:19]
	v_mfma_f32_16x16x32_bf16 v[60:63], v[152:155], v[188:191], v[60:63]
	v_mfma_f32_16x16x32_bf16 v[56:59], v[160:163], v[188:191], v[56:59]
	v_mfma_f32_16x16x32_bf16 v[52:55], v[152:155], v[196:199], v[52:55]
	v_mfma_f32_16x16x32_bf16 v[48:51], v[160:163], v[196:199], v[48:51]
	v_mfma_f32_16x16x32_bf16 v[36:39], v[152:155], v[204:207], v[36:39]
	v_mfma_f32_16x16x32_bf16 v[32:35], v[160:163], v[204:207], v[32:35]
	v_mfma_f32_16x16x32_bf16 v[20:23], v[152:155], v[212:215], v[20:23]
	v_mfma_f32_16x16x32_bf16 v[16:19], v[160:163], v[212:215], v[16:19]
	s_setprio 0
	s_setprio 1
	v_mfma_f32_16x16x32_bf16 v[44:47], v[164:167], v[184:187], v[44:47]
	v_mfma_f32_16x16x32_bf16 v[40:43], v[172:175], v[184:187], v[40:43]
	v_mfma_f32_16x16x32_bf16 v[28:31], v[164:167], v[192:195], v[28:31]
	v_mfma_f32_16x16x32_bf16 v[24:27], v[172:175], v[192:195], v[24:27]
	v_mfma_f32_16x16x32_bf16 v[12:15], v[164:167], v[200:203], v[12:15]
	v_mfma_f32_16x16x32_bf16 v[8:11], v[172:175], v[200:203], v[8:11]
	v_mfma_f32_16x16x32_bf16 v[4:7], v[164:167], v[208:211], v[4:7]
	v_mfma_f32_16x16x32_bf16 v[0:3], v[172:175], v[208:211], v[0:3]
	v_mfma_f32_16x16x32_bf16 v[44:47], v[168:171], v[188:191], v[44:47]
	v_mfma_f32_16x16x32_bf16 v[40:43], v[176:179], v[188:191], v[40:43]
	v_mfma_f32_16x16x32_bf16 v[28:31], v[168:171], v[196:199], v[28:31]
	v_mfma_f32_16x16x32_bf16 v[24:27], v[176:179], v[196:199], v[24:27]
	v_mfma_f32_16x16x32_bf16 v[12:15], v[168:171], v[204:207], v[12:15]
	v_mfma_f32_16x16x32_bf16 v[8:11], v[176:179], v[204:207], v[8:11]
	v_mfma_f32_16x16x32_bf16 v[4:7], v[168:171], v[212:215], v[4:7]
	v_mfma_f32_16x16x32_bf16 v[0:3], v[176:179], v[212:215], v[0:3]
	s_setprio 0
	s_barrier
	s_add_i32 s42, 0, 0x18000
	v_add_u32_e32 v147, s42, v143
	s_add_i32 s43, 0, 0x1c000
	ds_read_b128 v[148:151], v147
	ds_read_b128 v[152:155], v147 offset:1024
	ds_read_b128 v[156:159], v147 offset:2048
	ds_read_b128 v[160:163], v147 offset:3072
	v_add_u32_e32 v147, s43, v143
	ds_read_b128 v[164:167], v147
	ds_read_b128 v[168:171], v147 offset:1024
	ds_read_b128 v[172:175], v147 offset:2048
	ds_read_b128 v[176:179], v147 offset:3072
	s_add_u32 s22, s22, 0x80000
	s_addc_u32 s23, s23, 0
	s_mov_b32 m0, s25
	v_lshl_add_u64 v[222:223], s[22:23], 0, v[128:129]
	ds_read_b128 v[184:187], v146 offset:32768
	ds_read_b128 v[188:191], v146 offset:33792
	ds_read_b128 v[192:195], v146 offset:34816
	ds_read_b128 v[196:199], v146 offset:35840
	ds_read_b128 v[200:203], v146 offset:36864
	ds_read_b128 v[204:207], v146 offset:37888
	ds_read_b128 v[208:211], v146 offset:38912
	ds_read_b128 v[212:215], v146 offset:39936
	global_load_lds_dwordx4 v[222:223], off
	v_lshl_add_u64 v[222:223], s[22:23], 0, v[130:131]
	s_mov_b32 m0, s26
	s_nop 0
	global_load_lds_dwordx4 v[222:223], off
	s_nop 0
	s_waitcnt vmcnt(8)
	s_waitcnt lgkmcnt(0)
	s_barrier
	s_setprio 1
	s_waitcnt lgkmcnt(0)
	v_mfma_f32_16x16x32_bf16 v[124:127], v[148:151], v[184:187], v[124:127]
	v_mfma_f32_16x16x32_bf16 v[120:123], v[156:159], v[184:187], v[120:123]
	v_mfma_f32_16x16x32_bf16 v[116:119], v[148:151], v[192:195], v[116:119]
	v_mfma_f32_16x16x32_bf16 v[112:115], v[156:159], v[192:195], v[112:115]
	v_mfma_f32_16x16x32_bf16 v[100:103], v[148:151], v[200:203], v[100:103]
	v_mfma_f32_16x16x32_bf16 v[96:99], v[156:159], v[200:203], v[96:99]
	v_mfma_f32_16x16x32_bf16 v[84:87], v[148:151], v[208:211], v[84:87]
	v_mfma_f32_16x16x32_bf16 v[80:83], v[156:159], v[208:211], v[80:83]
	v_mfma_f32_16x16x32_bf16 v[124:127], v[152:155], v[188:191], v[124:127]
	v_mfma_f32_16x16x32_bf16 v[120:123], v[160:163], v[188:191], v[120:123]
	v_mfma_f32_16x16x32_bf16 v[116:119], v[152:155], v[196:199], v[116:119]
	v_mfma_f32_16x16x32_bf16 v[112:115], v[160:163], v[196:199], v[112:115]
	v_mfma_f32_16x16x32_bf16 v[100:103], v[152:155], v[204:207], v[100:103]
	v_mfma_f32_16x16x32_bf16 v[96:99], v[160:163], v[204:207], v[96:99]
	v_mfma_f32_16x16x32_bf16 v[84:87], v[152:155], v[212:215], v[84:87]
	v_mfma_f32_16x16x32_bf16 v[80:83], v[160:163], v[212:215], v[80:83]
	s_setprio 0
	s_setprio 1
	v_mfma_f32_16x16x32_bf16 v[108:111], v[164:167], v[184:187], v[108:111]
	v_mfma_f32_16x16x32_bf16 v[104:107], v[172:175], v[184:187], v[104:107]
	v_mfma_f32_16x16x32_bf16 v[92:95], v[164:167], v[192:195], v[92:95]
	v_mfma_f32_16x16x32_bf16 v[88:91], v[172:175], v[192:195], v[88:91]
	v_mfma_f32_16x16x32_bf16 v[76:79], v[164:167], v[200:203], v[76:79]
	v_mfma_f32_16x16x32_bf16 v[72:75], v[172:175], v[200:203], v[72:75]
	v_mfma_f32_16x16x32_bf16 v[68:71], v[164:167], v[208:211], v[68:71]
	v_mfma_f32_16x16x32_bf16 v[64:67], v[172:175], v[208:211], v[64:67]
	v_mfma_f32_16x16x32_bf16 v[108:111], v[168:171], v[188:191], v[108:111]
	v_mfma_f32_16x16x32_bf16 v[104:107], v[176:179], v[188:191], v[104:107]
	v_mfma_f32_16x16x32_bf16 v[92:95], v[168:171], v[196:199], v[92:95]
	v_mfma_f32_16x16x32_bf16 v[88:91], v[176:179], v[196:199], v[88:91]
	v_mfma_f32_16x16x32_bf16 v[76:79], v[168:171], v[204:207], v[76:79]
	v_mfma_f32_16x16x32_bf16 v[72:75], v[176:179], v[204:207], v[72:75]
	v_mfma_f32_16x16x32_bf16 v[68:71], v[168:171], v[212:215], v[68:71]
	v_mfma_f32_16x16x32_bf16 v[64:67], v[176:179], v[212:215], v[64:67]
	s_setprio 0
	s_barrier
	s_add_i32 s22, s42, s2
	v_lshl_add_u64 v[180:181], v[180:181], 0, s[6:7]
	s_mov_b32 m0, s22
	ds_read_b128 v[184:187], v146 offset:49152
	ds_read_b128 v[188:191], v146 offset:50176
	ds_read_b128 v[192:195], v146 offset:51200
	ds_read_b128 v[196:199], v146 offset:52224
	ds_read_b128 v[200:203], v146 offset:53248
	ds_read_b128 v[204:207], v146 offset:54272
	ds_read_b128 v[208:211], v146 offset:55296
	ds_read_b128 v[212:215], v146 offset:56320
	global_load_lds_dwordx4 v[180:181], off
	s_add_i32 m0, s22, 0x2000
	s_add_u32 s20, s20, 0x80080
	v_lshl_add_u64 v[180:181], v[216:217], 0, s[6:7]
	s_addc_u32 s21, s21, 0
	s_add_i32 s22, s43, s2
	global_load_lds_dwordx4 v[180:181], off
	v_lshl_add_u64 v[180:181], s[20:21], 0, v[128:129]
	s_mov_b32 m0, s22
	s_nop 0
	global_load_lds_dwordx4 v[180:181], off
	v_lshl_add_u64 v[180:181], s[20:21], 0, v[130:131]
	s_add_i32 m0, s22, 0x2000
	s_nop 0
	global_load_lds_dwordx4 v[180:181], off
	v_lshl_add_u64 v[180:181], v[218:219], 0, s[6:7]
	s_mov_b32 m0, s27
	s_nop 0
	global_load_lds_dwordx4 v[180:181], off
	v_lshl_add_u64 v[180:181], v[220:221], 0, s[6:7]
	s_mov_b32 m0, s28
	s_nop 0
	global_load_lds_dwordx4 v[180:181], off
	s_waitcnt vmcnt(8)
	s_waitcnt lgkmcnt(0)
	s_barrier
	s_setprio 1
	s_waitcnt lgkmcnt(0)
	v_mfma_f32_16x16x32_bf16 v[60:63], v[148:151], v[184:187], v[60:63]
	v_mfma_f32_16x16x32_bf16 v[56:59], v[156:159], v[184:187], v[56:59]
	v_mfma_f32_16x16x32_bf16 v[52:55], v[148:151], v[192:195], v[52:55]
	v_mfma_f32_16x16x32_bf16 v[48:51], v[156:159], v[192:195], v[48:51]
	v_mfma_f32_16x16x32_bf16 v[36:39], v[148:151], v[200:203], v[36:39]
	v_mfma_f32_16x16x32_bf16 v[32:35], v[156:159], v[200:203], v[32:35]
	v_mfma_f32_16x16x32_bf16 v[20:23], v[148:151], v[208:211], v[20:23]
	v_mfma_f32_16x16x32_bf16 v[16:19], v[156:159], v[208:211], v[16:19]
	v_mfma_f32_16x16x32_bf16 v[60:63], v[152:155], v[188:191], v[60:63]
	v_mfma_f32_16x16x32_bf16 v[56:59], v[160:163], v[188:191], v[56:59]
	v_mfma_f32_16x16x32_bf16 v[52:55], v[152:155], v[196:199], v[52:55]
	v_mfma_f32_16x16x32_bf16 v[48:51], v[160:163], v[196:199], v[48:51]
	v_mfma_f32_16x16x32_bf16 v[36:39], v[152:155], v[204:207], v[36:39]
	v_mfma_f32_16x16x32_bf16 v[32:35], v[160:163], v[204:207], v[32:35]
	v_mfma_f32_16x16x32_bf16 v[20:23], v[152:155], v[212:215], v[20:23]
	v_mfma_f32_16x16x32_bf16 v[16:19], v[160:163], v[212:215], v[16:19]
	s_setprio 0
	s_setprio 1
	v_mfma_f32_16x16x32_bf16 v[44:47], v[164:167], v[184:187], v[44:47]
	v_mfma_f32_16x16x32_bf16 v[40:43], v[172:175], v[184:187], v[40:43]
	v_mfma_f32_16x16x32_bf16 v[28:31], v[164:167], v[192:195], v[28:31]
	v_mfma_f32_16x16x32_bf16 v[24:27], v[172:175], v[192:195], v[24:27]
	v_mfma_f32_16x16x32_bf16 v[12:15], v[164:167], v[200:203], v[12:15]
	v_mfma_f32_16x16x32_bf16 v[8:11], v[172:175], v[200:203], v[8:11]
	v_mfma_f32_16x16x32_bf16 v[4:7], v[164:167], v[208:211], v[4:7]
	v_mfma_f32_16x16x32_bf16 v[0:3], v[172:175], v[208:211], v[0:3]
	v_mfma_f32_16x16x32_bf16 v[44:47], v[168:171], v[188:191], v[44:47]
	v_mfma_f32_16x16x32_bf16 v[40:43], v[176:179], v[188:191], v[40:43]
	v_mfma_f32_16x16x32_bf16 v[28:31], v[168:171], v[196:199], v[28:31]
	v_mfma_f32_16x16x32_bf16 v[24:27], v[176:179], v[196:199], v[24:27]
	v_mfma_f32_16x16x32_bf16 v[12:15], v[168:171], v[204:207], v[12:15]
	v_mfma_f32_16x16x32_bf16 v[8:11], v[176:179], v[204:207], v[8:11]
	v_mfma_f32_16x16x32_bf16 v[4:7], v[168:171], v[212:215], v[4:7]
	v_mfma_f32_16x16x32_bf16 v[0:3], v[176:179], v[212:215], v[0:3]
	s_setprio 0
	s_barrier
	s_add_i32 s41, s41, 2
	s_add_u32 s18, s18, 0x100
	s_addc_u32 s19, s19, 0
	s_add_u32 s39, s39, 0x100
	s_addc_u32 s40, s40, 0
	s_cmp_gt_u32 s41, 29
	s_cbranch_scc0 .LBB0_185
	s_nop 0
	s_nop 0
	s_nop 0
	s_nop 0
	s_nop 0
	s_nop 0
	s_nop 0
	s_nop 0
	s_nop 0
	s_nop 0
	s_nop 0
	s_nop 0
	s_nop 0
	s_nop 0
	s_and_b64 vcc, exec, s[8:9]
	s_cbranch_vccz .LBB0_188
	s_barrier

.LBB0_755:
	ds_read_b128 v[156:159], v166
	ds_read_b128 v[160:163], v166 offset:1024
	ds_read_b128 v[168:171], v166 offset:2048
	ds_read_b128 v[172:175], v166 offset:3072
	ds_read_b128 v[176:179], v167
	ds_read_b128 v[184:187], v167 offset:1024
	ds_read_b128 v[188:191], v167 offset:2048
	ds_read_b128 v[192:195], v167 offset:3072
	s_add_u32 s4, s28, s0
	s_addc_u32 s5, s29, s1
	s_add_u32 s4, s4, 0x4800100
	s_addc_u32 s5, s5, 0
	s_add_u32 s38, s33, s0
	s_addc_u32 s39, s36, s1
	s_cmpk_eq_i32 s0, 0xf00
	s_cselect_b32 s27, s10, s5
	s_cselect_b32 s26, s3, s4
	s_cselect_b32 s5, s11, s39
	s_cselect_b32 s4, s2, s38
	s_add_i32 s88, s45, 0xc000
	v_lshl_add_u64 v[180:181], v[128:129], 0, s[0:1]
	s_mov_b32 m0, s88
	s_add_i32 s89, s45, 0xe000
	ds_read_b128 v[196:199], v165
	ds_read_b128 v[200:203], v165 offset:1024
	ds_read_b128 v[204:207], v165 offset:2048
	ds_read_b128 v[208:211], v165 offset:3072
	ds_read_b128 v[212:215], v165 offset:4096
	ds_read_b128 v[216:219], v165 offset:5120
	ds_read_b128 v[220:223], v165 offset:6144
	ds_read_b128 v[224:227], v165 offset:7168
	global_load_lds_dwordx4 v[180:181], off
	v_lshl_add_u64 v[180:181], v[130:131], 0, s[0:1]
	s_mov_b32 m0, s89
	s_nop 0
	global_load_lds_dwordx4 v[180:181], off
	s_waitcnt vmcnt(8)
	s_waitcnt lgkmcnt(0)
	s_barrier
	s_setprio 1
	s_waitcnt lgkmcnt(0)
	v_mfma_f32_16x16x32_bf16 v[124:127], v[156:159], v[196:199], v[124:127]
	v_mfma_f32_16x16x32_bf16 v[120:123], v[168:171], v[196:199], v[120:123]
	v_mfma_f32_16x16x32_bf16 v[108:111], v[156:159], v[204:207], v[108:111]
	v_mfma_f32_16x16x32_bf16 v[104:107], v[168:171], v[204:207], v[104:107]
	v_mfma_f32_16x16x32_bf16 v[92:95], v[156:159], v[212:215], v[92:95]
	v_mfma_f32_16x16x32_bf16 v[88:91], v[168:171], v[212:215], v[88:91]
	v_mfma_f32_16x16x32_bf16 v[76:79], v[156:159], v[220:223], v[76:79]
	v_mfma_f32_16x16x32_bf16 v[72:75], v[168:171], v[220:223], v[72:75]
	v_mfma_f32_16x16x32_bf16 v[124:127], v[160:163], v[200:203], v[124:127]
	v_mfma_f32_16x16x32_bf16 v[120:123], v[172:175], v[200:203], v[120:123]
	v_mfma_f32_16x16x32_bf16 v[108:111], v[160:163], v[208:211], v[108:111]
	v_mfma_f32_16x16x32_bf16 v[104:107], v[172:175], v[208:211], v[104:107]
	v_mfma_f32_16x16x32_bf16 v[92:95], v[160:163], v[216:219], v[92:95]
	v_mfma_f32_16x16x32_bf16 v[88:91], v[172:175], v[216:219], v[88:91]
	v_mfma_f32_16x16x32_bf16 v[76:79], v[160:163], v[224:227], v[76:79]
	v_mfma_f32_16x16x32_bf16 v[72:75], v[172:175], v[224:227], v[72:75]
	s_setprio 0
	s_setprio 1
	v_mfma_f32_16x16x32_bf16 v[116:119], v[176:179], v[196:199], v[116:119]
	v_mfma_f32_16x16x32_bf16 v[112:115], v[188:191], v[196:199], v[112:115]
	v_mfma_f32_16x16x32_bf16 v[100:103], v[176:179], v[204:207], v[100:103]
	v_mfma_f32_16x16x32_bf16 v[96:99], v[188:191], v[204:207], v[96:99]
	v_mfma_f32_16x16x32_bf16 v[84:87], v[176:179], v[212:215], v[84:87]
	v_mfma_f32_16x16x32_bf16 v[80:83], v[188:191], v[212:215], v[80:83]
	v_mfma_f32_16x16x32_bf16 v[68:71], v[176:179], v[220:223], v[68:71]
	v_mfma_f32_16x16x32_bf16 v[64:67], v[188:191], v[220:223], v[64:67]
	v_mfma_f32_16x16x32_bf16 v[116:119], v[184:187], v[200:203], v[116:119]
	v_mfma_f32_16x16x32_bf16 v[112:115], v[192:195], v[200:203], v[112:115]
	v_mfma_f32_16x16x32_bf16 v[100:103], v[184:187], v[208:211], v[100:103]
	v_mfma_f32_16x16x32_bf16 v[96:99], v[192:195], v[208:211], v[96:99]
	v_mfma_f32_16x16x32_bf16 v[84:87], v[184:187], v[216:219], v[84:87]
	v_mfma_f32_16x16x32_bf16 v[80:83], v[192:195], v[216:219], v[80:83]
	v_mfma_f32_16x16x32_bf16 v[68:71], v[184:187], v[224:227], v[68:71]
	v_mfma_f32_16x16x32_bf16 v[64:67], v[192:195], v[224:227], v[64:67]
	s_setprio 0
	s_barrier
	s_add_i32 s90, s80, s44
	s_add_i32 s91, s90, 0x2000
	v_lshl_add_u64 v[228:229], s[4:5], 0, v[132:133]
	s_mov_b32 m0, s90
	s_add_u32 s38, s4, 0x80000
	ds_read_b128 v[196:199], v165 offset:16384
	ds_read_b128 v[200:203], v165 offset:17408
	ds_read_b128 v[204:207], v165 offset:18432
	ds_read_b128 v[208:211], v165 offset:19456
	ds_read_b128 v[212:215], v165 offset:20480
	ds_read_b128 v[216:219], v165 offset:21504
	ds_read_b128 v[220:223], v165 offset:22528
	ds_read_b128 v[224:227], v165 offset:23552
	global_load_lds_dwordx4 v[228:229], off
	v_lshl_add_u64 v[230:231], s[4:5], 0, v[134:135]
	s_mov_b32 m0, s91
	s_addc_u32 s39, s5, 0
	s_add_i32 s92, s81, s44
	global_load_lds_dwordx4 v[230:231], off
	v_lshl_add_u64 v[180:181], s[38:39], 0, v[132:133]
	s_mov_b32 m0, s92
	s_add_i32 s93, s92, 0x2000
	global_load_lds_dwordx4 v[180:181], off
	v_lshl_add_u64 v[180:181], s[38:39], 0, v[134:135]
	s_mov_b32 m0, s93
	v_lshl_add_u64 v[232:233], s[26:27], 0, v[132:133]
	global_load_lds_dwordx4 v[180:181], off
	s_mov_b32 m0, s45
	v_lshl_add_u64 v[234:235], s[26:27], 0, v[134:135]
	global_load_lds_dwordx4 v[232:233], off
	s_mov_b32 m0, s46
	s_nop 0
	global_load_lds_dwordx4 v[234:235], off
	s_nop 0
	s_waitcnt vmcnt(8)
	s_waitcnt lgkmcnt(0)
	s_barrier
	s_setprio 1
	s_waitcnt lgkmcnt(0)
	v_mfma_f32_16x16x32_bf16 v[60:63], v[156:159], v[196:199], v[60:63]
	v_mfma_f32_16x16x32_bf16 v[56:59], v[168:171], v[196:199], v[56:59]
	v_mfma_f32_16x16x32_bf16 v[44:47], v[156:159], v[204:207], v[44:47]
	v_mfma_f32_16x16x32_bf16 v[40:43], v[168:171], v[204:207], v[40:43]
	v_mfma_f32_16x16x32_bf16 v[28:31], v[156:159], v[212:215], v[28:31]
	v_mfma_f32_16x16x32_bf16 v[24:27], v[168:171], v[212:215], v[24:27]
	v_mfma_f32_16x16x32_bf16 v[12:15], v[156:159], v[220:223], v[12:15]
	v_mfma_f32_16x16x32_bf16 v[8:11], v[168:171], v[220:223], v[8:11]
	v_mfma_f32_16x16x32_bf16 v[60:63], v[160:163], v[200:203], v[60:63]
	v_mfma_f32_16x16x32_bf16 v[56:59], v[172:175], v[200:203], v[56:59]
	v_mfma_f32_16x16x32_bf16 v[44:47], v[160:163], v[208:211], v[44:47]
	v_mfma_f32_16x16x32_bf16 v[40:43], v[172:175], v[208:211], v[40:43]
	v_mfma_f32_16x16x32_bf16 v[28:31], v[160:163], v[216:219], v[28:31]
	v_mfma_f32_16x16x32_bf16 v[24:27], v[172:175], v[216:219], v[24:27]
	v_mfma_f32_16x16x32_bf16 v[12:15], v[160:163], v[224:227], v[12:15]
	v_mfma_f32_16x16x32_bf16 v[8:11], v[172:175], v[224:227], v[8:11]
	s_setprio 0
	s_setprio 1
	v_mfma_f32_16x16x32_bf16 v[52:55], v[176:179], v[196:199], v[52:55]
	v_mfma_f32_16x16x32_bf16 v[48:51], v[188:191], v[196:199], v[48:51]
	v_mfma_f32_16x16x32_bf16 v[36:39], v[176:179], v[204:207], v[36:39]
	v_mfma_f32_16x16x32_bf16 v[32:35], v[188:191], v[204:207], v[32:35]
	v_mfma_f32_16x16x32_bf16 v[20:23], v[176:179], v[212:215], v[20:23]
	v_mfma_f32_16x16x32_bf16 v[16:19], v[188:191], v[212:215], v[16:19]
	v_mfma_f32_16x16x32_bf16 v[4:7], v[176:179], v[220:223], v[4:7]
	v_mfma_f32_16x16x32_bf16 v[0:3], v[188:191], v[220:223], v[0:3]
	v_mfma_f32_16x16x32_bf16 v[52:55], v[184:187], v[200:203], v[52:55]
	v_mfma_f32_16x16x32_bf16 v[48:51], v[192:195], v[200:203], v[48:51]
	v_mfma_f32_16x16x32_bf16 v[36:39], v[184:187], v[208:211], v[36:39]
	v_mfma_f32_16x16x32_bf16 v[32:35], v[192:195], v[208:211], v[32:35]
	v_mfma_f32_16x16x32_bf16 v[20:23], v[184:187], v[216:219], v[20:23]
	v_mfma_f32_16x16x32_bf16 v[16:19], v[192:195], v[216:219], v[16:19]
	v_mfma_f32_16x16x32_bf16 v[4:7], v[184:187], v[224:227], v[4:7]
	v_mfma_f32_16x16x32_bf16 v[0:3], v[192:195], v[224:227], v[0:3]
	s_setprio 0
	s_barrier
	s_add_i32 s94, 0, 0x18000
	s_add_i32 s96, 0, 0x1c000
	v_add_u32_e32 v168, s94, v164
	v_add_u32_e32 v169, s96, v164
	ds_read_b128 v[156:159], v168
	ds_read_b128 v[160:163], v168 offset:1024
	ds_read_b128 v[170:173], v168 offset:2048
	ds_read_b128 v[174:177], v168 offset:3072
	ds_read_b128 v[178:181], v169
	ds_read_b128 v[184:187], v169 offset:1024
	ds_read_b128 v[188:191], v169 offset:2048
	ds_read_b128 v[192:195], v169 offset:3072
	s_add_u32 s26, s26, 0x80000
	s_addc_u32 s27, s27, 0
	s_mov_b32 m0, s47
	v_lshl_add_u64 v[236:237], s[26:27], 0, v[132:133]
	ds_read_b128 v[196:199], v165 offset:32768
	ds_read_b128 v[200:203], v165 offset:33792
	ds_read_b128 v[204:207], v165 offset:34816
	ds_read_b128 v[208:211], v165 offset:35840
	ds_read_b128 v[212:215], v165 offset:36864
	ds_read_b128 v[216:219], v165 offset:37888
	ds_read_b128 v[220:223], v165 offset:38912
	ds_read_b128 v[224:227], v165 offset:39936
	global_load_lds_dwordx4 v[236:237], off
	v_lshl_add_u64 v[236:237], s[26:27], 0, v[134:135]
	s_mov_b32 m0, s50
	s_nop 0
	global_load_lds_dwordx4 v[236:237], off
	s_nop 0
	s_waitcnt vmcnt(8)
	s_waitcnt lgkmcnt(0)
	s_barrier
	s_setprio 1
	s_waitcnt lgkmcnt(0)
	v_mfma_f32_16x16x32_bf16 v[124:127], v[156:159], v[196:199], v[124:127]
	v_mfma_f32_16x16x32_bf16 v[120:123], v[170:173], v[196:199], v[120:123]
	v_mfma_f32_16x16x32_bf16 v[108:111], v[156:159], v[204:207], v[108:111]
	v_mfma_f32_16x16x32_bf16 v[104:107], v[170:173], v[204:207], v[104:107]
	v_mfma_f32_16x16x32_bf16 v[92:95], v[156:159], v[212:215], v[92:95]
	v_mfma_f32_16x16x32_bf16 v[88:91], v[170:173], v[212:215], v[88:91]
	v_mfma_f32_16x16x32_bf16 v[76:79], v[156:159], v[220:223], v[76:79]
	v_mfma_f32_16x16x32_bf16 v[72:75], v[170:173], v[220:223], v[72:75]
	v_mfma_f32_16x16x32_bf16 v[124:127], v[160:163], v[200:203], v[124:127]
	v_mfma_f32_16x16x32_bf16 v[120:123], v[174:177], v[200:203], v[120:123]
	v_mfma_f32_16x16x32_bf16 v[108:111], v[160:163], v[208:211], v[108:111]
	v_mfma_f32_16x16x32_bf16 v[104:107], v[174:177], v[208:211], v[104:107]
	v_mfma_f32_16x16x32_bf16 v[92:95], v[160:163], v[216:219], v[92:95]
	v_mfma_f32_16x16x32_bf16 v[88:91], v[174:177], v[216:219], v[88:91]
	v_mfma_f32_16x16x32_bf16 v[76:79], v[160:163], v[224:227], v[76:79]
	v_mfma_f32_16x16x32_bf16 v[72:75], v[174:177], v[224:227], v[72:75]
	s_setprio 0
	s_setprio 1
	v_mfma_f32_16x16x32_bf16 v[116:119], v[178:181], v[196:199], v[116:119]
	v_mfma_f32_16x16x32_bf16 v[112:115], v[188:191], v[196:199], v[112:115]
	v_mfma_f32_16x16x32_bf16 v[100:103], v[178:181], v[204:207], v[100:103]
	v_mfma_f32_16x16x32_bf16 v[96:99], v[188:191], v[204:207], v[96:99]
	v_mfma_f32_16x16x32_bf16 v[84:87], v[178:181], v[212:215], v[84:87]
	v_mfma_f32_16x16x32_bf16 v[80:83], v[188:191], v[212:215], v[80:83]
	v_mfma_f32_16x16x32_bf16 v[68:71], v[178:181], v[220:223], v[68:71]
	v_mfma_f32_16x16x32_bf16 v[64:67], v[188:191], v[220:223], v[64:67]
	v_mfma_f32_16x16x32_bf16 v[116:119], v[184:187], v[200:203], v[116:119]
	v_mfma_f32_16x16x32_bf16 v[112:115], v[192:195], v[200:203], v[112:115]
	v_mfma_f32_16x16x32_bf16 v[100:103], v[184:187], v[208:211], v[100:103]
	v_mfma_f32_16x16x32_bf16 v[96:99], v[192:195], v[208:211], v[96:99]
	v_mfma_f32_16x16x32_bf16 v[84:87], v[184:187], v[216:219], v[84:87]
	v_mfma_f32_16x16x32_bf16 v[80:83], v[192:195], v[216:219], v[80:83]
	v_mfma_f32_16x16x32_bf16 v[68:71], v[184:187], v[224:227], v[68:71]
	v_mfma_f32_16x16x32_bf16 v[64:67], v[192:195], v[224:227], v[64:67]
	s_setprio 0
	s_barrier
	s_add_i32 s94, s94, s44
	s_add_i32 s95, s94, 0x2000
	v_lshl_add_u64 v[228:229], v[228:229], 0, s[18:19]
	s_mov_b32 m0, s94
	s_add_u32 s4, s4, 0x80080
	ds_read_b128 v[196:199], v165 offset:49152
	ds_read_b128 v[200:203], v165 offset:50176
	ds_read_b128 v[204:207], v165 offset:51200
	ds_read_b128 v[208:211], v165 offset:52224
	ds_read_b128 v[212:215], v165 offset:53248
	ds_read_b128 v[216:219], v165 offset:54272
	ds_read_b128 v[220:223], v165 offset:55296
	ds_read_b128 v[224:227], v165 offset:56320
	global_load_lds_dwordx4 v[228:229], off
	v_lshl_add_u64 v[228:229], v[230:231], 0, s[18:19]
	s_mov_b32 m0, s95
	s_addc_u32 s5, s5, 0
	s_add_i32 s96, s96, s44
	global_load_lds_dwordx4 v[228:229], off
	v_lshl_add_u64 v[228:229], s[4:5], 0, v[132:133]
	s_mov_b32 m0, s96
	s_add_i32 s97, s96, 0x2000
	global_load_lds_dwordx4 v[228:229], off
	v_lshl_add_u64 v[228:229], s[4:5], 0, v[134:135]
	s_mov_b32 m0, s97
	s_nop 0
	global_load_lds_dwordx4 v[228:229], off
	v_lshl_add_u64 v[228:229], v[232:233], 0, s[18:19]
	s_mov_b32 m0, s70
	s_nop 0
	global_load_lds_dwordx4 v[228:229], off
	v_lshl_add_u64 v[228:229], v[234:235], 0, s[18:19]
	s_mov_b32 m0, s71
	s_nop 0
	global_load_lds_dwordx4 v[228:229], off
	s_nop 0
	s_waitcnt vmcnt(8)
	s_waitcnt lgkmcnt(0)
	s_barrier
	s_setprio 1
	s_waitcnt lgkmcnt(0)
	v_mfma_f32_16x16x32_bf16 v[60:63], v[156:159], v[196:199], v[60:63]
	v_mfma_f32_16x16x32_bf16 v[56:59], v[170:173], v[196:199], v[56:59]
	v_mfma_f32_16x16x32_bf16 v[44:47], v[156:159], v[204:207], v[44:47]
	v_mfma_f32_16x16x32_bf16 v[40:43], v[170:173], v[204:207], v[40:43]
	v_mfma_f32_16x16x32_bf16 v[28:31], v[156:159], v[212:215], v[28:31]
	v_mfma_f32_16x16x32_bf16 v[24:27], v[170:173], v[212:215], v[24:27]
	v_mfma_f32_16x16x32_bf16 v[12:15], v[156:159], v[220:223], v[12:15]
	v_mfma_f32_16x16x32_bf16 v[8:11], v[170:173], v[220:223], v[8:11]
	v_mfma_f32_16x16x32_bf16 v[60:63], v[160:163], v[200:203], v[60:63]
	v_mfma_f32_16x16x32_bf16 v[56:59], v[174:177], v[200:203], v[56:59]
	v_mfma_f32_16x16x32_bf16 v[44:47], v[160:163], v[208:211], v[44:47]
	v_mfma_f32_16x16x32_bf16 v[40:43], v[174:177], v[208:211], v[40:43]
	v_mfma_f32_16x16x32_bf16 v[28:31], v[160:163], v[216:219], v[28:31]
	v_mfma_f32_16x16x32_bf16 v[24:27], v[174:177], v[216:219], v[24:27]
	v_mfma_f32_16x16x32_bf16 v[12:15], v[160:163], v[224:227], v[12:15]
	v_mfma_f32_16x16x32_bf16 v[8:11], v[174:177], v[224:227], v[8:11]
	s_setprio 0
	s_setprio 1
	v_mfma_f32_16x16x32_bf16 v[52:55], v[178:181], v[196:199], v[52:55]
	v_mfma_f32_16x16x32_bf16 v[48:51], v[188:191], v[196:199], v[48:51]
	v_mfma_f32_16x16x32_bf16 v[36:39], v[178:181], v[204:207], v[36:39]
	v_mfma_f32_16x16x32_bf16 v[32:35], v[188:191], v[204:207], v[32:35]
	v_mfma_f32_16x16x32_bf16 v[20:23], v[178:181], v[212:215], v[20:23]
	v_mfma_f32_16x16x32_bf16 v[16:19], v[188:191], v[212:215], v[16:19]
	v_mfma_f32_16x16x32_bf16 v[4:7], v[178:181], v[220:223], v[4:7]
	v_mfma_f32_16x16x32_bf16 v[0:3], v[188:191], v[220:223], v[0:3]
	v_mfma_f32_16x16x32_bf16 v[52:55], v[184:187], v[200:203], v[52:55]
	v_mfma_f32_16x16x32_bf16 v[48:51], v[192:195], v[200:203], v[48:51]
	v_mfma_f32_16x16x32_bf16 v[36:39], v[184:187], v[208:211], v[36:39]
	v_mfma_f32_16x16x32_bf16 v[32:35], v[192:195], v[208:211], v[32:35]
	v_mfma_f32_16x16x32_bf16 v[20:23], v[184:187], v[216:219], v[20:23]
	v_mfma_f32_16x16x32_bf16 v[16:19], v[192:195], v[216:219], v[16:19]
	v_mfma_f32_16x16x32_bf16 v[4:7], v[184:187], v[224:227], v[4:7]
	v_mfma_f32_16x16x32_bf16 v[0:3], v[192:195], v[224:227], v[0:3]
	s_setprio 0
	s_barrier
	s_add_i32 s37, s37, 2
	s_add_u32 s0, s0, 0x100
	s_addc_u32 s1, s1, 0
	s_cmp_gt_u32 s37, 29
	s_cbranch_scc0 .LBB0_755
	s_nop 0
	s_nop 0
	s_nop 0
	s_nop 0
	s_nop 0
	s_nop 0
	s_nop 0
	s_nop 0
	s_nop 0
	s_nop 0
	s_nop 0
	s_nop 0
	s_nop 0
	s_and_b64 vcc, exec, s[20:21]
	s_cbranch_vccz .LBB0_758
	s_barrier

.LBB0_761:
	ds_read_b128 v[156:159], v166
	ds_read_b128 v[160:163], v166 offset:1024
	ds_read_b128 v[170:173], v166 offset:2048
	ds_read_b128 v[174:177], v166 offset:3072
	ds_read_b128 v[178:181], v167
	ds_read_b128 v[184:187], v167 offset:1024
	ds_read_b128 v[188:191], v167 offset:2048
	ds_read_b128 v[192:195], v167 offset:3072
	s_add_u32 s34, s25, s30
	s_addc_u32 s35, s33, s31
	s_add_u32 s42, s34, 0x4800100
	s_addc_u32 s43, s35, 0
	s_add_u32 s48, s37, s30
	s_addc_u32 s49, s38, s31
	s_cmpk_eq_i32 s30, 0xf00
	s_cselect_b64 vcc, -1, 0
	s_and_b64 s[34:35], vcc, exec
	s_cselect_b32 s35, s3, s43
	s_cselect_b32 s34, s2, s42
	s_cselect_b32 s60, s84, 0x80000
	s_cselect_b32 s43, s11, s49
	s_cselect_b32 s42, s10, s48
	s_mov_b32 m0, s88
	v_lshl_add_u64 v[228:229], v[128:129], 0, s[30:31]
	ds_read_b128 v[196:199], v165
	ds_read_b128 v[200:203], v165 offset:1024
	ds_read_b128 v[204:207], v165 offset:2048
	ds_read_b128 v[208:211], v165 offset:3072
	ds_read_b128 v[212:215], v165 offset:4096
	ds_read_b128 v[216:219], v165 offset:5120
	ds_read_b128 v[220:223], v165 offset:6144
	ds_read_b128 v[224:227], v165 offset:7168
	global_load_lds_dwordx4 v[228:229], off
	v_lshl_add_u64 v[228:229], v[130:131], 0, s[30:31]
	s_mov_b32 m0, s89
	s_nop 0
	global_load_lds_dwordx4 v[228:229], off
	s_nop 0
	s_waitcnt vmcnt(8)
	s_waitcnt lgkmcnt(0)
	s_barrier
	s_setprio 1
	s_waitcnt lgkmcnt(0)
	v_mfma_f32_16x16x32_bf16 v[124:127], v[156:159], v[196:199], v[124:127]
	v_mfma_f32_16x16x32_bf16 v[120:123], v[170:173], v[196:199], v[120:123]
	v_mfma_f32_16x16x32_bf16 v[108:111], v[156:159], v[204:207], v[108:111]
	v_mfma_f32_16x16x32_bf16 v[104:107], v[170:173], v[204:207], v[104:107]
	v_mfma_f32_16x16x32_bf16 v[92:95], v[156:159], v[212:215], v[92:95]
	v_mfma_f32_16x16x32_bf16 v[88:91], v[170:173], v[212:215], v[88:91]
	v_mfma_f32_16x16x32_bf16 v[76:79], v[156:159], v[220:223], v[76:79]
	v_mfma_f32_16x16x32_bf16 v[72:75], v[170:173], v[220:223], v[72:75]
	v_mfma_f32_16x16x32_bf16 v[124:127], v[160:163], v[200:203], v[124:127]
	v_mfma_f32_16x16x32_bf16 v[120:123], v[174:177], v[200:203], v[120:123]
	v_mfma_f32_16x16x32_bf16 v[108:111], v[160:163], v[208:211], v[108:111]
	v_mfma_f32_16x16x32_bf16 v[104:107], v[174:177], v[208:211], v[104:107]
	v_mfma_f32_16x16x32_bf16 v[92:95], v[160:163], v[216:219], v[92:95]
	v_mfma_f32_16x16x32_bf16 v[88:91], v[174:177], v[216:219], v[88:91]
	v_mfma_f32_16x16x32_bf16 v[76:79], v[160:163], v[224:227], v[76:79]
	v_mfma_f32_16x16x32_bf16 v[72:75], v[174:177], v[224:227], v[72:75]
	s_setprio 0
	s_setprio 1
	v_mfma_f32_16x16x32_bf16 v[116:119], v[178:181], v[196:199], v[116:119]
	v_mfma_f32_16x16x32_bf16 v[112:115], v[188:191], v[196:199], v[112:115]
	v_mfma_f32_16x16x32_bf16 v[100:103], v[178:181], v[204:207], v[100:103]
	v_mfma_f32_16x16x32_bf16 v[96:99], v[188:191], v[204:207], v[96:99]
	v_mfma_f32_16x16x32_bf16 v[84:87], v[178:181], v[212:215], v[84:87]
	v_mfma_f32_16x16x32_bf16 v[80:83], v[188:191], v[212:215], v[80:83]
	v_mfma_f32_16x16x32_bf16 v[68:71], v[178:181], v[220:223], v[68:71]
	v_mfma_f32_16x16x32_bf16 v[64:67], v[188:191], v[220:223], v[64:67]
	v_mfma_f32_16x16x32_bf16 v[116:119], v[184:187], v[200:203], v[116:119]
	v_mfma_f32_16x16x32_bf16 v[112:115], v[192:195], v[200:203], v[112:115]
	v_mfma_f32_16x16x32_bf16 v[100:103], v[184:187], v[208:211], v[100:103]
	v_mfma_f32_16x16x32_bf16 v[96:99], v[192:195], v[208:211], v[96:99]
	v_mfma_f32_16x16x32_bf16 v[84:87], v[184:187], v[216:219], v[84:87]
	v_mfma_f32_16x16x32_bf16 v[80:83], v[192:195], v[216:219], v[80:83]
	v_mfma_f32_16x16x32_bf16 v[68:71], v[184:187], v[224:227], v[68:71]
	v_mfma_f32_16x16x32_bf16 v[64:67], v[192:195], v[224:227], v[64:67]
	s_setprio 0
	s_barrier
	s_mov_b32 m0, s90
	v_cndmask_b32_e32 v136, v132, v138, vcc
	ds_read_b128 v[196:199], v165 offset:16384
	ds_read_b128 v[200:203], v165 offset:17408
	ds_read_b128 v[204:207], v165 offset:18432
	ds_read_b128 v[208:211], v165 offset:19456
	ds_read_b128 v[212:215], v165 offset:20480
	ds_read_b128 v[216:219], v165 offset:21504
	ds_read_b128 v[220:223], v165 offset:22528
	ds_read_b128 v[224:227], v165 offset:23552
	global_load_lds_dwordx4 v136, s[42:43]
	v_cndmask_b32_e32 v228, v134, v140, vcc
	s_mov_b32 m0, s91
	s_add_u32 s48, s42, s60
	global_load_lds_dwordx4 v228, s[42:43]
	s_addc_u32 s49, s43, 0
	s_mov_b32 m0, s92
	v_mov_b32_e32 v229, v137
	global_load_lds_dwordx4 v136, s[48:49]
	s_mov_b32 m0, s93
	v_lshl_add_u64 v[230:231], s[42:43], 0, v[136:137]
	global_load_lds_dwordx4 v228, s[48:49]
	s_mov_b32 m0, s45
	v_lshl_add_u64 v[232:233], s[42:43], 0, v[228:229]
	global_load_lds_dwordx4 v136, s[34:35]
	s_mov_b32 m0, s46
	v_lshl_add_u64 v[234:235], s[48:49], 0, v[136:137]
	global_load_lds_dwordx4 v228, s[34:35]
	s_waitcnt vmcnt(8)
	s_waitcnt lgkmcnt(0)
	v_lshl_add_u64 v[236:237], s[48:49], 0, v[228:229]
	v_lshl_add_u64 v[238:239], s[34:35], 0, v[136:137]
	v_lshl_add_u64 v[240:241], s[34:35], 0, v[228:229]
	s_barrier
	s_setprio 1
	s_waitcnt lgkmcnt(0)
	v_mfma_f32_16x16x32_bf16 v[60:63], v[156:159], v[196:199], v[60:63]
	v_mfma_f32_16x16x32_bf16 v[56:59], v[170:173], v[196:199], v[56:59]
	v_mfma_f32_16x16x32_bf16 v[44:47], v[156:159], v[204:207], v[44:47]
	v_mfma_f32_16x16x32_bf16 v[40:43], v[170:173], v[204:207], v[40:43]
	v_mfma_f32_16x16x32_bf16 v[28:31], v[156:159], v[212:215], v[28:31]
	v_mfma_f32_16x16x32_bf16 v[24:27], v[170:173], v[212:215], v[24:27]
	v_mfma_f32_16x16x32_bf16 v[12:15], v[156:159], v[220:223], v[12:15]
	v_mfma_f32_16x16x32_bf16 v[8:11], v[170:173], v[220:223], v[8:11]
	v_mfma_f32_16x16x32_bf16 v[60:63], v[160:163], v[200:203], v[60:63]
	v_mfma_f32_16x16x32_bf16 v[56:59], v[174:177], v[200:203], v[56:59]
	v_mfma_f32_16x16x32_bf16 v[44:47], v[160:163], v[208:211], v[44:47]
	v_mfma_f32_16x16x32_bf16 v[40:43], v[174:177], v[208:211], v[40:43]
	v_mfma_f32_16x16x32_bf16 v[28:31], v[160:163], v[216:219], v[28:31]
	v_mfma_f32_16x16x32_bf16 v[24:27], v[174:177], v[216:219], v[24:27]
	v_mfma_f32_16x16x32_bf16 v[12:15], v[160:163], v[224:227], v[12:15]
	v_mfma_f32_16x16x32_bf16 v[8:11], v[174:177], v[224:227], v[8:11]
	s_setprio 0
	s_setprio 1
	v_mfma_f32_16x16x32_bf16 v[52:55], v[178:181], v[196:199], v[52:55]
	v_mfma_f32_16x16x32_bf16 v[48:51], v[188:191], v[196:199], v[48:51]
	v_mfma_f32_16x16x32_bf16 v[36:39], v[178:181], v[204:207], v[36:39]
	v_mfma_f32_16x16x32_bf16 v[32:35], v[188:191], v[204:207], v[32:35]
	v_mfma_f32_16x16x32_bf16 v[20:23], v[178:181], v[212:215], v[20:23]
	v_mfma_f32_16x16x32_bf16 v[16:19], v[188:191], v[212:215], v[16:19]
	v_mfma_f32_16x16x32_bf16 v[4:7], v[178:181], v[220:223], v[4:7]
	v_mfma_f32_16x16x32_bf16 v[0:3], v[188:191], v[220:223], v[0:3]
	v_mfma_f32_16x16x32_bf16 v[52:55], v[184:187], v[200:203], v[52:55]
	v_mfma_f32_16x16x32_bf16 v[48:51], v[192:195], v[200:203], v[48:51]
	v_mfma_f32_16x16x32_bf16 v[36:39], v[184:187], v[208:211], v[36:39]
	v_mfma_f32_16x16x32_bf16 v[32:35], v[192:195], v[208:211], v[32:35]
	v_mfma_f32_16x16x32_bf16 v[20:23], v[184:187], v[216:219], v[20:23]
	v_mfma_f32_16x16x32_bf16 v[16:19], v[192:195], v[216:219], v[16:19]
	v_mfma_f32_16x16x32_bf16 v[4:7], v[184:187], v[224:227], v[4:7]
	v_mfma_f32_16x16x32_bf16 v[0:3], v[192:195], v[224:227], v[0:3]
	s_setprio 0
	s_barrier
	ds_read_b128 v[156:159], v168
	ds_read_b128 v[160:163], v168 offset:1024
	ds_read_b128 v[170:173], v168 offset:2048
	ds_read_b128 v[174:177], v168 offset:3072
	ds_read_b128 v[178:181], v169
	ds_read_b128 v[184:187], v169 offset:1024
	ds_read_b128 v[188:191], v169 offset:2048
	ds_read_b128 v[192:195], v169 offset:3072
	s_add_u32 s34, s34, s60
	s_addc_u32 s35, s35, 0
	s_mov_b32 m0, s47
	ds_read_b128 v[196:199], v165 offset:32768
	ds_read_b128 v[200:203], v165 offset:33792
	ds_read_b128 v[204:207], v165 offset:34816
	ds_read_b128 v[208:211], v165 offset:35840
	ds_read_b128 v[212:215], v165 offset:36864
	ds_read_b128 v[216:219], v165 offset:37888
	ds_read_b128 v[220:223], v165 offset:38912
	ds_read_b128 v[224:227], v165 offset:39936
	global_load_lds_dwordx4 v136, s[34:35]
	s_mov_b32 m0, s50
	s_nop 0
	global_load_lds_dwordx4 v228, s[34:35]
	s_waitcnt vmcnt(8)
	s_waitcnt lgkmcnt(0)
	s_barrier
	s_setprio 1
	s_waitcnt lgkmcnt(0)
	v_mfma_f32_16x16x32_bf16 v[124:127], v[156:159], v[196:199], v[124:127]
	v_mfma_f32_16x16x32_bf16 v[120:123], v[170:173], v[196:199], v[120:123]
	v_mfma_f32_16x16x32_bf16 v[108:111], v[156:159], v[204:207], v[108:111]
	v_mfma_f32_16x16x32_bf16 v[104:107], v[170:173], v[204:207], v[104:107]
	v_mfma_f32_16x16x32_bf16 v[92:95], v[156:159], v[212:215], v[92:95]
	v_mfma_f32_16x16x32_bf16 v[88:91], v[170:173], v[212:215], v[88:91]
	v_mfma_f32_16x16x32_bf16 v[76:79], v[156:159], v[220:223], v[76:79]
	v_mfma_f32_16x16x32_bf16 v[72:75], v[170:173], v[220:223], v[72:75]
	v_mfma_f32_16x16x32_bf16 v[124:127], v[160:163], v[200:203], v[124:127]
	v_mfma_f32_16x16x32_bf16 v[120:123], v[174:177], v[200:203], v[120:123]
	v_mfma_f32_16x16x32_bf16 v[108:111], v[160:163], v[208:211], v[108:111]
	v_mfma_f32_16x16x32_bf16 v[104:107], v[174:177], v[208:211], v[104:107]
	v_mfma_f32_16x16x32_bf16 v[92:95], v[160:163], v[216:219], v[92:95]
	v_mfma_f32_16x16x32_bf16 v[88:91], v[174:177], v[216:219], v[88:91]
	v_mfma_f32_16x16x32_bf16 v[76:79], v[160:163], v[224:227], v[76:79]
	v_mfma_f32_16x16x32_bf16 v[72:75], v[174:177], v[224:227], v[72:75]
	s_setprio 0
	s_setprio 1
	v_mfma_f32_16x16x32_bf16 v[116:119], v[178:181], v[196:199], v[116:119]
	v_mfma_f32_16x16x32_bf16 v[112:115], v[188:191], v[196:199], v[112:115]
	v_mfma_f32_16x16x32_bf16 v[100:103], v[178:181], v[204:207], v[100:103]
	v_mfma_f32_16x16x32_bf16 v[96:99], v[188:191], v[204:207], v[96:99]
	v_mfma_f32_16x16x32_bf16 v[84:87], v[178:181], v[212:215], v[84:87]
	v_mfma_f32_16x16x32_bf16 v[80:83], v[188:191], v[212:215], v[80:83]
	v_mfma_f32_16x16x32_bf16 v[68:71], v[178:181], v[220:223], v[68:71]
	v_mfma_f32_16x16x32_bf16 v[64:67], v[188:191], v[220:223], v[64:67]
	v_mfma_f32_16x16x32_bf16 v[116:119], v[184:187], v[200:203], v[116:119]
	v_mfma_f32_16x16x32_bf16 v[112:115], v[192:195], v[200:203], v[112:115]
	v_mfma_f32_16x16x32_bf16 v[100:103], v[184:187], v[208:211], v[100:103]
	v_mfma_f32_16x16x32_bf16 v[96:99], v[192:195], v[208:211], v[96:99]
	v_mfma_f32_16x16x32_bf16 v[84:87], v[184:187], v[216:219], v[84:87]
	v_mfma_f32_16x16x32_bf16 v[80:83], v[192:195], v[216:219], v[80:83]
	v_mfma_f32_16x16x32_bf16 v[68:71], v[184:187], v[224:227], v[68:71]
	v_mfma_f32_16x16x32_bf16 v[64:67], v[192:195], v[224:227], v[64:67]
	s_setprio 0
	s_barrier
	s_mov_b32 m0, s94
	v_lshl_add_u64 v[228:229], v[230:231], 0, s[18:19]
	ds_read_b128 v[196:199], v165 offset:49152
	ds_read_b128 v[200:203], v165 offset:50176
	ds_read_b128 v[204:207], v165 offset:51200
	ds_read_b128 v[208:211], v165 offset:52224
	ds_read_b128 v[212:215], v165 offset:53248
	ds_read_b128 v[216:219], v165 offset:54272
	ds_read_b128 v[220:223], v165 offset:55296
	ds_read_b128 v[224:227], v165 offset:56320
	global_load_lds_dwordx4 v[228:229], off
	v_lshl_add_u64 v[228:229], v[232:233], 0, s[18:19]
	s_mov_b32 m0, s95
	s_nop 0
	global_load_lds_dwordx4 v[228:229], off
	v_lshl_add_u64 v[228:229], v[234:235], 0, s[18:19]
	s_mov_b32 m0, s96
	s_nop 0
	global_load_lds_dwordx4 v[228:229], off
	v_lshl_add_u64 v[228:229], v[236:237], 0, s[18:19]
	s_mov_b32 m0, s97
	s_nop 0
	global_load_lds_dwordx4 v[228:229], off
	v_lshl_add_u64 v[228:229], v[238:239], 0, s[18:19]
	s_mov_b32 m0, s70
	s_nop 0
	global_load_lds_dwordx4 v[228:229], off
	v_lshl_add_u64 v[228:229], v[240:241], 0, s[18:19]
	s_mov_b32 m0, s71
	s_nop 0
	global_load_lds_dwordx4 v[228:229], off
	s_waitcnt vmcnt(8)
	s_waitcnt lgkmcnt(0)
	s_barrier
	s_setprio 1
	s_waitcnt lgkmcnt(0)
	v_mfma_f32_16x16x32_bf16 v[60:63], v[156:159], v[196:199], v[60:63]
	v_mfma_f32_16x16x32_bf16 v[56:59], v[170:173], v[196:199], v[56:59]
	v_mfma_f32_16x16x32_bf16 v[44:47], v[156:159], v[204:207], v[44:47]
	v_mfma_f32_16x16x32_bf16 v[40:43], v[170:173], v[204:207], v[40:43]
	v_mfma_f32_16x16x32_bf16 v[28:31], v[156:159], v[212:215], v[28:31]
	v_mfma_f32_16x16x32_bf16 v[24:27], v[170:173], v[212:215], v[24:27]
	v_mfma_f32_16x16x32_bf16 v[12:15], v[156:159], v[220:223], v[12:15]
	v_mfma_f32_16x16x32_bf16 v[8:11], v[170:173], v[220:223], v[8:11]
	v_mfma_f32_16x16x32_bf16 v[60:63], v[160:163], v[200:203], v[60:63]
	v_mfma_f32_16x16x32_bf16 v[56:59], v[174:177], v[200:203], v[56:59]
	v_mfma_f32_16x16x32_bf16 v[44:47], v[160:163], v[208:211], v[44:47]
	v_mfma_f32_16x16x32_bf16 v[40:43], v[174:177], v[208:211], v[40:43]
	v_mfma_f32_16x16x32_bf16 v[28:31], v[160:163], v[216:219], v[28:31]
	v_mfma_f32_16x16x32_bf16 v[24:27], v[174:177], v[216:219], v[24:27]
	v_mfma_f32_16x16x32_bf16 v[12:15], v[160:163], v[224:227], v[12:15]
	v_mfma_f32_16x16x32_bf16 v[8:11], v[174:177], v[224:227], v[8:11]
	s_setprio 0
	s_setprio 1
	v_mfma_f32_16x16x32_bf16 v[52:55], v[178:181], v[196:199], v[52:55]
	v_mfma_f32_16x16x32_bf16 v[48:51], v[188:191], v[196:199], v[48:51]
	v_mfma_f32_16x16x32_bf16 v[36:39], v[178:181], v[204:207], v[36:39]
	v_mfma_f32_16x16x32_bf16 v[32:35], v[188:191], v[204:207], v[32:35]
	v_mfma_f32_16x16x32_bf16 v[20:23], v[178:181], v[212:215], v[20:23]
	v_mfma_f32_16x16x32_bf16 v[16:19], v[188:191], v[212:215], v[16:19]
	v_mfma_f32_16x16x32_bf16 v[4:7], v[178:181], v[220:223], v[4:7]
	v_mfma_f32_16x16x32_bf16 v[0:3], v[188:191], v[220:223], v[0:3]
	v_mfma_f32_16x16x32_bf16 v[52:55], v[184:187], v[200:203], v[52:55]
	v_mfma_f32_16x16x32_bf16 v[48:51], v[192:195], v[200:203], v[48:51]
	v_mfma_f32_16x16x32_bf16 v[36:39], v[184:187], v[208:211], v[36:39]
	v_mfma_f32_16x16x32_bf16 v[32:35], v[192:195], v[208:211], v[32:35]
	v_mfma_f32_16x16x32_bf16 v[20:23], v[184:187], v[216:219], v[20:23]
	v_mfma_f32_16x16x32_bf16 v[16:19], v[192:195], v[216:219], v[16:19]
	v_mfma_f32_16x16x32_bf16 v[4:7], v[184:187], v[224:227], v[4:7]
	v_mfma_f32_16x16x32_bf16 v[0:3], v[192:195], v[224:227], v[0:3]
	s_setprio 0
	s_barrier
	s_add_i32 s39, s39, 2
	s_add_u32 s30, s30, 0x100
	s_addc_u32 s31, s31, 0
	s_cmp_gt_u32 s39, 29
	s_cbranch_scc0 .LBB0_761
	s_nop 0
	s_nop 0
	s_nop 0
	s_nop 0
	s_nop 0
	s_nop 0
	s_nop 0
	s_nop 0
	s_nop 0
	s_nop 0
	s_nop 0
	s_nop 0
	s_nop 0
	s_nop 0
	s_nop 0
	s_and_b64 vcc, exec, s[20:21]
	s_cbranch_vccz .LBB0_764
	s_barrier

.LBB0_767:
	ds_read_b128 v[156:159], v166
	ds_read_b128 v[160:163], v166 offset:1024
	ds_read_b128 v[170:173], v166 offset:2048
	ds_read_b128 v[174:177], v166 offset:3072
	ds_read_b128 v[178:181], v167
	ds_read_b128 v[184:187], v167 offset:1024
	ds_read_b128 v[188:191], v167 offset:2048
	ds_read_b128 v[192:195], v167 offset:3072
	s_add_u32 s36, s25, s34
	s_addc_u32 s37, s10, s35
	s_add_u32 s36, s36, 0x16800100
	s_addc_u32 s37, s37, 0
	s_add_u32 s49, s2, s34
	s_addc_u32 s60, s3, s35
	s_cmpk_eq_i32 s34, 0x700
	s_cselect_b32 s39, s33, s37
	s_cselect_b32 s38, s43, s36
	s_cselect_b32 s37, s42, s60
	s_cselect_b32 s36, s11, s49
	s_mov_b32 m0, s88
	v_lshl_add_u64 v[228:229], v[128:129], 0, s[34:35]
	ds_read_b128 v[196:199], v165
	ds_read_b128 v[200:203], v165 offset:1024
	ds_read_b128 v[204:207], v165 offset:2048
	ds_read_b128 v[208:211], v165 offset:3072
	ds_read_b128 v[212:215], v165 offset:4096
	ds_read_b128 v[216:219], v165 offset:5120
	ds_read_b128 v[220:223], v165 offset:6144
	ds_read_b128 v[224:227], v165 offset:7168
	global_load_lds_dwordx4 v[228:229], off
	v_lshl_add_u64 v[228:229], v[130:131], 0, s[34:35]
	s_mov_b32 m0, s89
	s_nop 0
	global_load_lds_dwordx4 v[228:229], off
	s_waitcnt vmcnt(8)
	s_waitcnt lgkmcnt(0)
	s_barrier
	s_setprio 1
	s_waitcnt lgkmcnt(0)
	v_mfma_f32_16x16x32_bf16 v[8:11], v[156:159], v[196:199], v[8:11]
	v_mfma_f32_16x16x32_bf16 v[12:15], v[170:173], v[196:199], v[12:15]
	v_mfma_f32_16x16x32_bf16 v[40:43], v[156:159], v[204:207], v[40:43]
	v_mfma_f32_16x16x32_bf16 v[44:47], v[170:173], v[204:207], v[44:47]
	v_mfma_f32_16x16x32_bf16 v[64:67], v[156:159], v[212:215], v[64:67]
	v_mfma_f32_16x16x32_bf16 v[68:71], v[170:173], v[212:215], v[68:71]
	v_mfma_f32_16x16x32_bf16 v[100:103], v[156:159], v[220:223], v[100:103]
	v_mfma_f32_16x16x32_bf16 v[104:107], v[170:173], v[220:223], v[104:107]
	v_mfma_f32_16x16x32_bf16 v[8:11], v[160:163], v[200:203], v[8:11]
	v_mfma_f32_16x16x32_bf16 v[12:15], v[174:177], v[200:203], v[12:15]
	v_mfma_f32_16x16x32_bf16 v[40:43], v[160:163], v[208:211], v[40:43]
	v_mfma_f32_16x16x32_bf16 v[44:47], v[174:177], v[208:211], v[44:47]
	v_mfma_f32_16x16x32_bf16 v[64:67], v[160:163], v[216:219], v[64:67]
	v_mfma_f32_16x16x32_bf16 v[68:71], v[174:177], v[216:219], v[68:71]
	v_mfma_f32_16x16x32_bf16 v[100:103], v[160:163], v[224:227], v[100:103]
	v_mfma_f32_16x16x32_bf16 v[104:107], v[174:177], v[224:227], v[104:107]
	s_setprio 0
	s_setprio 1
	v_mfma_f32_16x16x32_bf16 v[28:31], v[178:181], v[196:199], v[28:31]
	v_mfma_f32_16x16x32_bf16 v[32:35], v[188:191], v[196:199], v[32:35]
	v_mfma_f32_16x16x32_bf16 v[48:51], v[178:181], v[204:207], v[48:51]
	v_mfma_f32_16x16x32_bf16 v[52:55], v[188:191], v[204:207], v[52:55]
	v_mfma_f32_16x16x32_bf16 v[80:83], v[178:181], v[212:215], v[80:83]
	v_mfma_f32_16x16x32_bf16 v[84:87], v[188:191], v[212:215], v[84:87]
	v_mfma_f32_16x16x32_bf16 v[108:111], v[178:181], v[220:223], v[108:111]
	v_mfma_f32_16x16x32_bf16 v[112:115], v[188:191], v[220:223], v[112:115]
	v_mfma_f32_16x16x32_bf16 v[28:31], v[184:187], v[200:203], v[28:31]
	v_mfma_f32_16x16x32_bf16 v[32:35], v[192:195], v[200:203], v[32:35]
	v_mfma_f32_16x16x32_bf16 v[48:51], v[184:187], v[208:211], v[48:51]
	v_mfma_f32_16x16x32_bf16 v[52:55], v[192:195], v[208:211], v[52:55]
	v_mfma_f32_16x16x32_bf16 v[80:83], v[184:187], v[216:219], v[80:83]
	v_mfma_f32_16x16x32_bf16 v[84:87], v[192:195], v[216:219], v[84:87]
	v_mfma_f32_16x16x32_bf16 v[108:111], v[184:187], v[224:227], v[108:111]
	v_mfma_f32_16x16x32_bf16 v[112:115], v[192:195], v[224:227], v[112:115]
	s_setprio 0
	s_barrier
	s_mov_b32 m0, s90
	v_lshl_add_u64 v[228:229], s[36:37], 0, v[138:139]
	s_add_u32 s60, s36, 0x40000
	ds_read_b128 v[196:199], v165 offset:16384
	ds_read_b128 v[200:203], v165 offset:17408
	ds_read_b128 v[204:207], v165 offset:18432
	ds_read_b128 v[208:211], v165 offset:19456
	ds_read_b128 v[212:215], v165 offset:20480
	ds_read_b128 v[216:219], v165 offset:21504
	ds_read_b128 v[220:223], v165 offset:22528
	ds_read_b128 v[224:227], v165 offset:23552
	global_load_lds_dwordx4 v[228:229], off
	v_lshl_add_u64 v[230:231], s[36:37], 0, v[140:141]
	s_mov_b32 m0, s91
	s_addc_u32 s61, s37, 0
	global_load_lds_dwordx4 v[230:231], off
	v_lshl_add_u64 v[232:233], s[60:61], 0, v[138:139]
	s_mov_b32 m0, s92
	v_lshl_add_u64 v[234:235], s[38:39], 0, v[140:141]
	global_load_lds_dwordx4 v[232:233], off
	v_lshl_add_u64 v[232:233], s[60:61], 0, v[140:141]
	s_mov_b32 m0, s93
	s_nop 0
	global_load_lds_dwordx4 v[232:233], off
	v_lshl_add_u64 v[232:233], s[38:39], 0, v[138:139]
	s_mov_b32 m0, s45
	s_nop 0
	global_load_lds_dwordx4 v[232:233], off
	s_mov_b32 m0, s46
	s_nop 0
	global_load_lds_dwordx4 v[234:235], off
	s_nop 0
	s_waitcnt vmcnt(8)
	s_waitcnt lgkmcnt(0)
	s_barrier
	s_setprio 1
	s_waitcnt lgkmcnt(0)
	v_mfma_f32_16x16x32_bf16 v[124:127], v[156:159], v[196:199], v[124:127]
	v_mfma_f32_16x16x32_bf16 v[120:123], v[170:173], v[196:199], v[120:123]
	v_mfma_f32_16x16x32_bf16 v[92:95], v[156:159], v[204:207], v[92:95]
	v_mfma_f32_16x16x32_bf16 v[88:91], v[170:173], v[204:207], v[88:91]
	v_mfma_f32_16x16x32_bf16 v[60:63], v[156:159], v[212:215], v[60:63]
	v_mfma_f32_16x16x32_bf16 v[56:59], v[170:173], v[212:215], v[56:59]
	v_mfma_f32_16x16x32_bf16 v[20:23], v[156:159], v[220:223], v[20:23]
	v_mfma_f32_16x16x32_bf16 v[16:19], v[170:173], v[220:223], v[16:19]
	v_mfma_f32_16x16x32_bf16 v[124:127], v[160:163], v[200:203], v[124:127]
	v_mfma_f32_16x16x32_bf16 v[120:123], v[174:177], v[200:203], v[120:123]
	v_mfma_f32_16x16x32_bf16 v[92:95], v[160:163], v[208:211], v[92:95]
	v_mfma_f32_16x16x32_bf16 v[88:91], v[174:177], v[208:211], v[88:91]
	v_mfma_f32_16x16x32_bf16 v[60:63], v[160:163], v[216:219], v[60:63]
	v_mfma_f32_16x16x32_bf16 v[56:59], v[174:177], v[216:219], v[56:59]
	v_mfma_f32_16x16x32_bf16 v[20:23], v[160:163], v[224:227], v[20:23]
	v_mfma_f32_16x16x32_bf16 v[16:19], v[174:177], v[224:227], v[16:19]
	s_setprio 0
	s_setprio 1
	v_mfma_f32_16x16x32_bf16 v[116:119], v[178:181], v[196:199], v[116:119]
	v_mfma_f32_16x16x32_bf16 v[96:99], v[188:191], v[196:199], v[96:99]
	v_mfma_f32_16x16x32_bf16 v[76:79], v[178:181], v[204:207], v[76:79]
	v_mfma_f32_16x16x32_bf16 v[72:75], v[188:191], v[204:207], v[72:75]
	v_mfma_f32_16x16x32_bf16 v[36:39], v[178:181], v[212:215], v[36:39]
	v_mfma_f32_16x16x32_bf16 v[24:27], v[188:191], v[212:215], v[24:27]
	v_mfma_f32_16x16x32_bf16 v[4:7], v[178:181], v[220:223], v[4:7]
	v_mfma_f32_16x16x32_bf16 v[0:3], v[188:191], v[220:223], v[0:3]
	v_mfma_f32_16x16x32_bf16 v[116:119], v[184:187], v[200:203], v[116:119]
	v_mfma_f32_16x16x32_bf16 v[96:99], v[192:195], v[200:203], v[96:99]
	v_mfma_f32_16x16x32_bf16 v[76:79], v[184:187], v[208:211], v[76:79]
	v_mfma_f32_16x16x32_bf16 v[72:75], v[192:195], v[208:211], v[72:75]
	v_mfma_f32_16x16x32_bf16 v[36:39], v[184:187], v[216:219], v[36:39]
	v_mfma_f32_16x16x32_bf16 v[24:27], v[192:195], v[216:219], v[24:27]
	v_mfma_f32_16x16x32_bf16 v[4:7], v[184:187], v[224:227], v[4:7]
	v_mfma_f32_16x16x32_bf16 v[0:3], v[192:195], v[224:227], v[0:3]
	s_setprio 0
	s_barrier
	ds_read_b128 v[156:159], v168
	ds_read_b128 v[160:163], v168 offset:1024
	ds_read_b128 v[170:173], v168 offset:2048
	ds_read_b128 v[174:177], v168 offset:3072
	ds_read_b128 v[178:181], v169
	ds_read_b128 v[184:187], v169 offset:1024
	ds_read_b128 v[188:191], v169 offset:2048
	ds_read_b128 v[192:195], v169 offset:3072
	s_add_u32 s38, s38, 0x40000
	s_addc_u32 s39, s39, 0
	s_mov_b32 m0, s47
	v_lshl_add_u64 v[236:237], s[38:39], 0, v[138:139]
	ds_read_b128 v[196:199], v165 offset:32768
	ds_read_b128 v[200:203], v165 offset:33792
	ds_read_b128 v[204:207], v165 offset:34816
	ds_read_b128 v[208:211], v165 offset:35840
	ds_read_b128 v[212:215], v165 offset:36864
	ds_read_b128 v[216:219], v165 offset:37888
	ds_read_b128 v[220:223], v165 offset:38912
	ds_read_b128 v[224:227], v165 offset:39936
	global_load_lds_dwordx4 v[236:237], off
	v_lshl_add_u64 v[236:237], s[38:39], 0, v[140:141]
	s_mov_b32 m0, s50
	s_nop 0
	global_load_lds_dwordx4 v[236:237], off
	s_nop 0
	s_waitcnt vmcnt(8)
	s_waitcnt lgkmcnt(0)
	s_barrier
	s_setprio 1
	s_waitcnt lgkmcnt(0)
	v_mfma_f32_16x16x32_bf16 v[8:11], v[156:159], v[196:199], v[8:11]
	v_mfma_f32_16x16x32_bf16 v[12:15], v[170:173], v[196:199], v[12:15]
	v_mfma_f32_16x16x32_bf16 v[40:43], v[156:159], v[204:207], v[40:43]
	v_mfma_f32_16x16x32_bf16 v[44:47], v[170:173], v[204:207], v[44:47]
	v_mfma_f32_16x16x32_bf16 v[64:67], v[156:159], v[212:215], v[64:67]
	v_mfma_f32_16x16x32_bf16 v[68:71], v[170:173], v[212:215], v[68:71]
	v_mfma_f32_16x16x32_bf16 v[100:103], v[156:159], v[220:223], v[100:103]
	v_mfma_f32_16x16x32_bf16 v[104:107], v[170:173], v[220:223], v[104:107]
	v_mfma_f32_16x16x32_bf16 v[8:11], v[160:163], v[200:203], v[8:11]
	v_mfma_f32_16x16x32_bf16 v[12:15], v[174:177], v[200:203], v[12:15]
	v_mfma_f32_16x16x32_bf16 v[40:43], v[160:163], v[208:211], v[40:43]
	v_mfma_f32_16x16x32_bf16 v[44:47], v[174:177], v[208:211], v[44:47]
	v_mfma_f32_16x16x32_bf16 v[64:67], v[160:163], v[216:219], v[64:67]
	v_mfma_f32_16x16x32_bf16 v[68:71], v[174:177], v[216:219], v[68:71]
	v_mfma_f32_16x16x32_bf16 v[100:103], v[160:163], v[224:227], v[100:103]
	v_mfma_f32_16x16x32_bf16 v[104:107], v[174:177], v[224:227], v[104:107]
	s_setprio 0
	s_setprio 1
	v_mfma_f32_16x16x32_bf16 v[28:31], v[178:181], v[196:199], v[28:31]
	v_mfma_f32_16x16x32_bf16 v[32:35], v[188:191], v[196:199], v[32:35]
	v_mfma_f32_16x16x32_bf16 v[48:51], v[178:181], v[204:207], v[48:51]
	v_mfma_f32_16x16x32_bf16 v[52:55], v[188:191], v[204:207], v[52:55]
	v_mfma_f32_16x16x32_bf16 v[80:83], v[178:181], v[212:215], v[80:83]
	v_mfma_f32_16x16x32_bf16 v[84:87], v[188:191], v[212:215], v[84:87]
	v_mfma_f32_16x16x32_bf16 v[108:111], v[178:181], v[220:223], v[108:111]
	v_mfma_f32_16x16x32_bf16 v[112:115], v[188:191], v[220:223], v[112:115]
	v_mfma_f32_16x16x32_bf16 v[28:31], v[184:187], v[200:203], v[28:31]
	v_mfma_f32_16x16x32_bf16 v[32:35], v[192:195], v[200:203], v[32:35]
	v_mfma_f32_16x16x32_bf16 v[48:51], v[184:187], v[208:211], v[48:51]
	v_mfma_f32_16x16x32_bf16 v[52:55], v[192:195], v[208:211], v[52:55]
	v_mfma_f32_16x16x32_bf16 v[80:83], v[184:187], v[216:219], v[80:83]
	v_mfma_f32_16x16x32_bf16 v[84:87], v[192:195], v[216:219], v[84:87]
	v_mfma_f32_16x16x32_bf16 v[108:111], v[184:187], v[224:227], v[108:111]
	v_mfma_f32_16x16x32_bf16 v[112:115], v[192:195], v[224:227], v[112:115]
	s_setprio 0
	s_barrier
	s_mov_b32 m0, s94
	v_lshl_add_u64 v[228:229], v[228:229], 0, s[18:19]
	s_add_u32 s36, s36, 0x40080
	ds_read_b128 v[196:199], v165 offset:49152
	ds_read_b128 v[200:203], v165 offset:50176
	ds_read_b128 v[204:207], v165 offset:51200
	ds_read_b128 v[208:211], v165 offset:52224
	ds_read_b128 v[212:215], v165 offset:53248
	ds_read_b128 v[216:219], v165 offset:54272
	ds_read_b128 v[220:223], v165 offset:55296
	ds_read_b128 v[224:227], v165 offset:56320
	global_load_lds_dwordx4 v[228:229], off
	v_lshl_add_u64 v[228:229], v[230:231], 0, s[18:19]
	s_mov_b32 m0, s95
	s_addc_u32 s37, s37, 0
	global_load_lds_dwordx4 v[228:229], off
	v_lshl_add_u64 v[228:229], s[36:37], 0, v[138:139]
	s_mov_b32 m0, s96
	s_nop 0
	global_load_lds_dwordx4 v[228:229], off
	v_lshl_add_u64 v[228:229], s[36:37], 0, v[140:141]
	s_mov_b32 m0, s97
	s_nop 0
	global_load_lds_dwordx4 v[228:229], off
	v_lshl_add_u64 v[228:229], v[232:233], 0, s[18:19]
	s_mov_b32 m0, s70
	s_nop 0
	global_load_lds_dwordx4 v[228:229], off
	v_lshl_add_u64 v[228:229], v[234:235], 0, s[18:19]
	s_mov_b32 m0, s71
	s_nop 0
	global_load_lds_dwordx4 v[228:229], off
	s_waitcnt vmcnt(8)
	s_waitcnt lgkmcnt(0)
	s_barrier
	s_setprio 1
	s_waitcnt lgkmcnt(0)
	v_mfma_f32_16x16x32_bf16 v[124:127], v[156:159], v[196:199], v[124:127]
	v_mfma_f32_16x16x32_bf16 v[120:123], v[170:173], v[196:199], v[120:123]
	v_mfma_f32_16x16x32_bf16 v[92:95], v[156:159], v[204:207], v[92:95]
	v_mfma_f32_16x16x32_bf16 v[88:91], v[170:173], v[204:207], v[88:91]
	v_mfma_f32_16x16x32_bf16 v[60:63], v[156:159], v[212:215], v[60:63]
	v_mfma_f32_16x16x32_bf16 v[56:59], v[170:173], v[212:215], v[56:59]
	v_mfma_f32_16x16x32_bf16 v[20:23], v[156:159], v[220:223], v[20:23]
	v_mfma_f32_16x16x32_bf16 v[16:19], v[170:173], v[220:223], v[16:19]
	v_mfma_f32_16x16x32_bf16 v[124:127], v[160:163], v[200:203], v[124:127]
	v_mfma_f32_16x16x32_bf16 v[120:123], v[174:177], v[200:203], v[120:123]
	v_mfma_f32_16x16x32_bf16 v[92:95], v[160:163], v[208:211], v[92:95]
	v_mfma_f32_16x16x32_bf16 v[88:91], v[174:177], v[208:211], v[88:91]
	v_mfma_f32_16x16x32_bf16 v[60:63], v[160:163], v[216:219], v[60:63]
	v_mfma_f32_16x16x32_bf16 v[56:59], v[174:177], v[216:219], v[56:59]
	v_mfma_f32_16x16x32_bf16 v[20:23], v[160:163], v[224:227], v[20:23]
	v_mfma_f32_16x16x32_bf16 v[16:19], v[174:177], v[224:227], v[16:19]
	s_setprio 0
	s_setprio 1
	v_mfma_f32_16x16x32_bf16 v[116:119], v[178:181], v[196:199], v[116:119]
	v_mfma_f32_16x16x32_bf16 v[96:99], v[188:191], v[196:199], v[96:99]
	v_mfma_f32_16x16x32_bf16 v[76:79], v[178:181], v[204:207], v[76:79]
	v_mfma_f32_16x16x32_bf16 v[72:75], v[188:191], v[204:207], v[72:75]
	v_mfma_f32_16x16x32_bf16 v[36:39], v[178:181], v[212:215], v[36:39]
	v_mfma_f32_16x16x32_bf16 v[24:27], v[188:191], v[212:215], v[24:27]
	v_mfma_f32_16x16x32_bf16 v[4:7], v[178:181], v[220:223], v[4:7]
	v_mfma_f32_16x16x32_bf16 v[0:3], v[188:191], v[220:223], v[0:3]
	v_mfma_f32_16x16x32_bf16 v[116:119], v[184:187], v[200:203], v[116:119]
	v_mfma_f32_16x16x32_bf16 v[96:99], v[192:195], v[200:203], v[96:99]
	v_mfma_f32_16x16x32_bf16 v[76:79], v[184:187], v[208:211], v[76:79]
	v_mfma_f32_16x16x32_bf16 v[72:75], v[192:195], v[208:211], v[72:75]
	v_mfma_f32_16x16x32_bf16 v[36:39], v[184:187], v[216:219], v[36:39]
	v_mfma_f32_16x16x32_bf16 v[24:27], v[192:195], v[216:219], v[24:27]
	v_mfma_f32_16x16x32_bf16 v[4:7], v[184:187], v[224:227], v[4:7]
	v_mfma_f32_16x16x32_bf16 v[0:3], v[192:195], v[224:227], v[0:3]
	s_setprio 0
	s_barrier
	s_add_i32 s48, s48, 2
	s_add_u32 s34, s34, 0x100
	s_addc_u32 s35, s35, 0
	s_cmp_gt_u32 s48, 13
	s_cbranch_scc0 .LBB0_767
	s_nop 0
	s_nop 0
	s_nop 0
	s_nop 0
	s_nop 0
	s_nop 0
	s_nop 0
	s_nop 0
	s_nop 0
	s_nop 0
	s_nop 0
	s_nop 0
	s_nop 0
	s_nop 0
	s_and_b64 vcc, exec, s[20:21]
	s_cbranch_vccz .LBB0_770
	s_barrier

.LBB0_773:
	ds_read_b128 v[156:159], v166
	ds_read_b128 v[160:163], v166 offset:1024
	ds_read_b128 v[170:173], v166 offset:2048
	ds_read_b128 v[174:177], v166 offset:3072
	ds_read_b128 v[178:181], v167
	ds_read_b128 v[184:187], v167 offset:1024
	ds_read_b128 v[188:191], v167 offset:2048
	ds_read_b128 v[192:195], v167 offset:3072
	s_add_u32 s28, s25, s26
	s_addc_u32 s29, s10, s27
	s_add_u32 s34, s28, 0x18800100
	s_addc_u32 s35, s29, 0
	s_add_u32 s60, s48, s26
	s_addc_u32 s61, s49, s27
	s_cmpk_eq_i32 s26, 0x700
	s_cselect_b64 vcc, -1, 0
	s_and_b64 s[28:29], vcc, exec
	s_cselect_b32 s29, s33, s35
	s_cselect_b32 s28, s43, s34
	s_cselect_b32 s87, 0x80000, s84
	s_cselect_b32 s35, s42, s61
	s_cselect_b32 s34, s11, s60
	s_mov_b32 m0, s88
	v_lshl_add_u64 v[228:229], v[128:129], 0, s[26:27]
	ds_read_b128 v[196:199], v165
	ds_read_b128 v[200:203], v165 offset:1024
	ds_read_b128 v[204:207], v165 offset:2048
	ds_read_b128 v[208:211], v165 offset:3072
	ds_read_b128 v[212:215], v165 offset:4096
	ds_read_b128 v[216:219], v165 offset:5120
	ds_read_b128 v[220:223], v165 offset:6144
	ds_read_b128 v[224:227], v165 offset:7168
	global_load_lds_dwordx4 v[228:229], off
	v_lshl_add_u64 v[228:229], v[130:131], 0, s[26:27]
	s_mov_b32 m0, s89
	s_nop 0
	global_load_lds_dwordx4 v[228:229], off
	s_nop 0
	s_waitcnt vmcnt(8)
	s_waitcnt lgkmcnt(0)
	s_barrier
	s_setprio 1
	s_waitcnt lgkmcnt(0)
	v_mfma_f32_16x16x32_bf16 v[8:11], v[156:159], v[196:199], v[8:11]
	v_mfma_f32_16x16x32_bf16 v[12:15], v[170:173], v[196:199], v[12:15]
	v_mfma_f32_16x16x32_bf16 v[40:43], v[156:159], v[204:207], v[40:43]
	v_mfma_f32_16x16x32_bf16 v[44:47], v[170:173], v[204:207], v[44:47]
	v_mfma_f32_16x16x32_bf16 v[64:67], v[156:159], v[212:215], v[64:67]
	v_mfma_f32_16x16x32_bf16 v[68:71], v[170:173], v[212:215], v[68:71]
	v_mfma_f32_16x16x32_bf16 v[100:103], v[156:159], v[220:223], v[100:103]
	v_mfma_f32_16x16x32_bf16 v[104:107], v[170:173], v[220:223], v[104:107]
	v_mfma_f32_16x16x32_bf16 v[8:11], v[160:163], v[200:203], v[8:11]
	v_mfma_f32_16x16x32_bf16 v[12:15], v[174:177], v[200:203], v[12:15]
	v_mfma_f32_16x16x32_bf16 v[40:43], v[160:163], v[208:211], v[40:43]
	v_mfma_f32_16x16x32_bf16 v[44:47], v[174:177], v[208:211], v[44:47]
	v_mfma_f32_16x16x32_bf16 v[64:67], v[160:163], v[216:219], v[64:67]
	v_mfma_f32_16x16x32_bf16 v[68:71], v[174:177], v[216:219], v[68:71]
	v_mfma_f32_16x16x32_bf16 v[100:103], v[160:163], v[224:227], v[100:103]
	v_mfma_f32_16x16x32_bf16 v[104:107], v[174:177], v[224:227], v[104:107]
	s_setprio 0
	s_setprio 1
	v_mfma_f32_16x16x32_bf16 v[28:31], v[178:181], v[196:199], v[28:31]
	v_mfma_f32_16x16x32_bf16 v[32:35], v[188:191], v[196:199], v[32:35]
	v_mfma_f32_16x16x32_bf16 v[48:51], v[178:181], v[204:207], v[48:51]
	v_mfma_f32_16x16x32_bf16 v[52:55], v[188:191], v[204:207], v[52:55]
	v_mfma_f32_16x16x32_bf16 v[80:83], v[178:181], v[212:215], v[80:83]
	v_mfma_f32_16x16x32_bf16 v[84:87], v[188:191], v[212:215], v[84:87]
	v_mfma_f32_16x16x32_bf16 v[108:111], v[178:181], v[220:223], v[108:111]
	v_mfma_f32_16x16x32_bf16 v[112:115], v[188:191], v[220:223], v[112:115]
	v_mfma_f32_16x16x32_bf16 v[28:31], v[184:187], v[200:203], v[28:31]
	v_mfma_f32_16x16x32_bf16 v[32:35], v[192:195], v[200:203], v[32:35]
	v_mfma_f32_16x16x32_bf16 v[48:51], v[184:187], v[208:211], v[48:51]
	v_mfma_f32_16x16x32_bf16 v[52:55], v[192:195], v[208:211], v[52:55]
	v_mfma_f32_16x16x32_bf16 v[80:83], v[184:187], v[216:219], v[80:83]
	v_mfma_f32_16x16x32_bf16 v[84:87], v[192:195], v[216:219], v[84:87]
	v_mfma_f32_16x16x32_bf16 v[108:111], v[184:187], v[224:227], v[108:111]
	v_mfma_f32_16x16x32_bf16 v[112:115], v[192:195], v[224:227], v[112:115]
	s_setprio 0
	s_barrier
	s_mov_b32 m0, s90
	v_cndmask_b32_e32 v136, v138, v132, vcc
	ds_read_b128 v[196:199], v165 offset:16384
	ds_read_b128 v[200:203], v165 offset:17408
	ds_read_b128 v[204:207], v165 offset:18432
	ds_read_b128 v[208:211], v165 offset:19456
	ds_read_b128 v[212:215], v165 offset:20480
	ds_read_b128 v[216:219], v165 offset:21504
	ds_read_b128 v[220:223], v165 offset:22528
	ds_read_b128 v[224:227], v165 offset:23552
	global_load_lds_dwordx4 v136, s[34:35]
	v_cndmask_b32_e32 v228, v140, v134, vcc
	s_mov_b32 m0, s91
	s_add_u32 s60, s34, s87
	global_load_lds_dwordx4 v228, s[34:35]
	s_addc_u32 s61, s35, 0
	s_mov_b32 m0, s92
	v_mov_b32_e32 v229, v137
	global_load_lds_dwordx4 v136, s[60:61]
	s_mov_b32 m0, s93
	v_lshl_add_u64 v[230:231], s[34:35], 0, v[136:137]
	global_load_lds_dwordx4 v228, s[60:61]
	s_mov_b32 m0, s45
	v_lshl_add_u64 v[232:233], s[34:35], 0, v[228:229]
	global_load_lds_dwordx4 v136, s[28:29]
	s_mov_b32 m0, s46
	v_lshl_add_u64 v[234:235], s[60:61], 0, v[136:137]
	global_load_lds_dwordx4 v228, s[28:29]
	s_waitcnt vmcnt(8)
	s_waitcnt lgkmcnt(0)
	v_lshl_add_u64 v[236:237], s[60:61], 0, v[228:229]
	v_lshl_add_u64 v[238:239], s[28:29], 0, v[136:137]
	v_lshl_add_u64 v[240:241], s[28:29], 0, v[228:229]
	s_barrier
	s_setprio 1
	s_waitcnt lgkmcnt(0)
	v_mfma_f32_16x16x32_bf16 v[124:127], v[156:159], v[196:199], v[124:127]
	v_mfma_f32_16x16x32_bf16 v[120:123], v[170:173], v[196:199], v[120:123]
	v_mfma_f32_16x16x32_bf16 v[92:95], v[156:159], v[204:207], v[92:95]
	v_mfma_f32_16x16x32_bf16 v[88:91], v[170:173], v[204:207], v[88:91]
	v_mfma_f32_16x16x32_bf16 v[60:63], v[156:159], v[212:215], v[60:63]
	v_mfma_f32_16x16x32_bf16 v[56:59], v[170:173], v[212:215], v[56:59]
	v_mfma_f32_16x16x32_bf16 v[20:23], v[156:159], v[220:223], v[20:23]
	v_mfma_f32_16x16x32_bf16 v[16:19], v[170:173], v[220:223], v[16:19]
	v_mfma_f32_16x16x32_bf16 v[124:127], v[160:163], v[200:203], v[124:127]
	v_mfma_f32_16x16x32_bf16 v[120:123], v[174:177], v[200:203], v[120:123]
	v_mfma_f32_16x16x32_bf16 v[92:95], v[160:163], v[208:211], v[92:95]
	v_mfma_f32_16x16x32_bf16 v[88:91], v[174:177], v[208:211], v[88:91]
	v_mfma_f32_16x16x32_bf16 v[60:63], v[160:163], v[216:219], v[60:63]
	v_mfma_f32_16x16x32_bf16 v[56:59], v[174:177], v[216:219], v[56:59]
	v_mfma_f32_16x16x32_bf16 v[20:23], v[160:163], v[224:227], v[20:23]
	v_mfma_f32_16x16x32_bf16 v[16:19], v[174:177], v[224:227], v[16:19]
	s_setprio 0
	s_setprio 1
	v_mfma_f32_16x16x32_bf16 v[116:119], v[178:181], v[196:199], v[116:119]
	v_mfma_f32_16x16x32_bf16 v[96:99], v[188:191], v[196:199], v[96:99]
	v_mfma_f32_16x16x32_bf16 v[76:79], v[178:181], v[204:207], v[76:79]
	v_mfma_f32_16x16x32_bf16 v[72:75], v[188:191], v[204:207], v[72:75]
	v_mfma_f32_16x16x32_bf16 v[36:39], v[178:181], v[212:215], v[36:39]
	v_mfma_f32_16x16x32_bf16 v[24:27], v[188:191], v[212:215], v[24:27]
	v_mfma_f32_16x16x32_bf16 v[4:7], v[178:181], v[220:223], v[4:7]
	v_mfma_f32_16x16x32_bf16 v[0:3], v[188:191], v[220:223], v[0:3]
	v_mfma_f32_16x16x32_bf16 v[116:119], v[184:187], v[200:203], v[116:119]
	v_mfma_f32_16x16x32_bf16 v[96:99], v[192:195], v[200:203], v[96:99]
	v_mfma_f32_16x16x32_bf16 v[76:79], v[184:187], v[208:211], v[76:79]
	v_mfma_f32_16x16x32_bf16 v[72:75], v[192:195], v[208:211], v[72:75]
	v_mfma_f32_16x16x32_bf16 v[36:39], v[184:187], v[216:219], v[36:39]
	v_mfma_f32_16x16x32_bf16 v[24:27], v[192:195], v[216:219], v[24:27]
	v_mfma_f32_16x16x32_bf16 v[4:7], v[184:187], v[224:227], v[4:7]
	v_mfma_f32_16x16x32_bf16 v[0:3], v[192:195], v[224:227], v[0:3]
	s_setprio 0
	s_barrier
	ds_read_b128 v[156:159], v168
	ds_read_b128 v[160:163], v168 offset:1024
	ds_read_b128 v[170:173], v168 offset:2048
	ds_read_b128 v[174:177], v168 offset:3072
	ds_read_b128 v[178:181], v169
	ds_read_b128 v[184:187], v169 offset:1024
	ds_read_b128 v[188:191], v169 offset:2048
	ds_read_b128 v[192:195], v169 offset:3072
	s_add_u32 s28, s28, s87
	s_addc_u32 s29, s29, 0
	s_mov_b32 m0, s47
	ds_read_b128 v[196:199], v165 offset:32768
	ds_read_b128 v[200:203], v165 offset:33792
	ds_read_b128 v[204:207], v165 offset:34816
	ds_read_b128 v[208:211], v165 offset:35840
	ds_read_b128 v[212:215], v165 offset:36864
	ds_read_b128 v[216:219], v165 offset:37888
	ds_read_b128 v[220:223], v165 offset:38912
	ds_read_b128 v[224:227], v165 offset:39936
	global_load_lds_dwordx4 v136, s[28:29]
	s_mov_b32 m0, s50
	s_nop 0
	global_load_lds_dwordx4 v228, s[28:29]
	s_waitcnt vmcnt(8)
	s_waitcnt lgkmcnt(0)
	s_barrier
	s_setprio 1
	s_waitcnt lgkmcnt(0)
	v_mfma_f32_16x16x32_bf16 v[8:11], v[156:159], v[196:199], v[8:11]
	v_mfma_f32_16x16x32_bf16 v[12:15], v[170:173], v[196:199], v[12:15]
	v_mfma_f32_16x16x32_bf16 v[40:43], v[156:159], v[204:207], v[40:43]
	v_mfma_f32_16x16x32_bf16 v[44:47], v[170:173], v[204:207], v[44:47]
	v_mfma_f32_16x16x32_bf16 v[64:67], v[156:159], v[212:215], v[64:67]
	v_mfma_f32_16x16x32_bf16 v[68:71], v[170:173], v[212:215], v[68:71]
	v_mfma_f32_16x16x32_bf16 v[100:103], v[156:159], v[220:223], v[100:103]
	v_mfma_f32_16x16x32_bf16 v[104:107], v[170:173], v[220:223], v[104:107]
	v_mfma_f32_16x16x32_bf16 v[8:11], v[160:163], v[200:203], v[8:11]
	v_mfma_f32_16x16x32_bf16 v[12:15], v[174:177], v[200:203], v[12:15]
	v_mfma_f32_16x16x32_bf16 v[40:43], v[160:163], v[208:211], v[40:43]
	v_mfma_f32_16x16x32_bf16 v[44:47], v[174:177], v[208:211], v[44:47]
	v_mfma_f32_16x16x32_bf16 v[64:67], v[160:163], v[216:219], v[64:67]
	v_mfma_f32_16x16x32_bf16 v[68:71], v[174:177], v[216:219], v[68:71]
	v_mfma_f32_16x16x32_bf16 v[100:103], v[160:163], v[224:227], v[100:103]
	v_mfma_f32_16x16x32_bf16 v[104:107], v[174:177], v[224:227], v[104:107]
	s_setprio 0
	s_setprio 1
	v_mfma_f32_16x16x32_bf16 v[28:31], v[178:181], v[196:199], v[28:31]
	v_mfma_f32_16x16x32_bf16 v[32:35], v[188:191], v[196:199], v[32:35]
	v_mfma_f32_16x16x32_bf16 v[48:51], v[178:181], v[204:207], v[48:51]
	v_mfma_f32_16x16x32_bf16 v[52:55], v[188:191], v[204:207], v[52:55]
	v_mfma_f32_16x16x32_bf16 v[80:83], v[178:181], v[212:215], v[80:83]
	v_mfma_f32_16x16x32_bf16 v[84:87], v[188:191], v[212:215], v[84:87]
	v_mfma_f32_16x16x32_bf16 v[108:111], v[178:181], v[220:223], v[108:111]
	v_mfma_f32_16x16x32_bf16 v[112:115], v[188:191], v[220:223], v[112:115]
	v_mfma_f32_16x16x32_bf16 v[28:31], v[184:187], v[200:203], v[28:31]
	v_mfma_f32_16x16x32_bf16 v[32:35], v[192:195], v[200:203], v[32:35]
	v_mfma_f32_16x16x32_bf16 v[48:51], v[184:187], v[208:211], v[48:51]
	v_mfma_f32_16x16x32_bf16 v[52:55], v[192:195], v[208:211], v[52:55]
	v_mfma_f32_16x16x32_bf16 v[80:83], v[184:187], v[216:219], v[80:83]
	v_mfma_f32_16x16x32_bf16 v[84:87], v[192:195], v[216:219], v[84:87]
	v_mfma_f32_16x16x32_bf16 v[108:111], v[184:187], v[224:227], v[108:111]
	v_mfma_f32_16x16x32_bf16 v[112:115], v[192:195], v[224:227], v[112:115]
	s_setprio 0
	s_barrier
	s_mov_b32 m0, s94
	v_lshl_add_u64 v[228:229], v[230:231], 0, s[18:19]
	ds_read_b128 v[196:199], v165 offset:49152
	ds_read_b128 v[200:203], v165 offset:50176
	ds_read_b128 v[204:207], v165 offset:51200
	ds_read_b128 v[208:211], v165 offset:52224
	ds_read_b128 v[212:215], v165 offset:53248
	ds_read_b128 v[216:219], v165 offset:54272
	ds_read_b128 v[220:223], v165 offset:55296
	ds_read_b128 v[224:227], v165 offset:56320
	global_load_lds_dwordx4 v[228:229], off
	v_lshl_add_u64 v[228:229], v[232:233], 0, s[18:19]
	s_mov_b32 m0, s95
	s_nop 0
	global_load_lds_dwordx4 v[228:229], off
	v_lshl_add_u64 v[228:229], v[234:235], 0, s[18:19]
	s_mov_b32 m0, s96
	s_nop 0
	global_load_lds_dwordx4 v[228:229], off
	v_lshl_add_u64 v[228:229], v[236:237], 0, s[18:19]
	s_mov_b32 m0, s97
	s_nop 0
	global_load_lds_dwordx4 v[228:229], off
	v_lshl_add_u64 v[228:229], v[238:239], 0, s[18:19]
	s_mov_b32 m0, s70
	s_nop 0
	global_load_lds_dwordx4 v[228:229], off
	v_lshl_add_u64 v[228:229], v[240:241], 0, s[18:19]
	s_mov_b32 m0, s71
	s_nop 0
	global_load_lds_dwordx4 v[228:229], off
	s_waitcnt vmcnt(8)
	s_waitcnt lgkmcnt(0)
	s_barrier
	s_setprio 1
	s_waitcnt lgkmcnt(0)
	v_mfma_f32_16x16x32_bf16 v[124:127], v[156:159], v[196:199], v[124:127]
	v_mfma_f32_16x16x32_bf16 v[120:123], v[170:173], v[196:199], v[120:123]
	v_mfma_f32_16x16x32_bf16 v[92:95], v[156:159], v[204:207], v[92:95]
	v_mfma_f32_16x16x32_bf16 v[88:91], v[170:173], v[204:207], v[88:91]
	v_mfma_f32_16x16x32_bf16 v[60:63], v[156:159], v[212:215], v[60:63]
	v_mfma_f32_16x16x32_bf16 v[56:59], v[170:173], v[212:215], v[56:59]
	v_mfma_f32_16x16x32_bf16 v[20:23], v[156:159], v[220:223], v[20:23]
	v_mfma_f32_16x16x32_bf16 v[16:19], v[170:173], v[220:223], v[16:19]
	v_mfma_f32_16x16x32_bf16 v[124:127], v[160:163], v[200:203], v[124:127]
	v_mfma_f32_16x16x32_bf16 v[120:123], v[174:177], v[200:203], v[120:123]
	v_mfma_f32_16x16x32_bf16 v[92:95], v[160:163], v[208:211], v[92:95]
	v_mfma_f32_16x16x32_bf16 v[88:91], v[174:177], v[208:211], v[88:91]
	v_mfma_f32_16x16x32_bf16 v[60:63], v[160:163], v[216:219], v[60:63]
	v_mfma_f32_16x16x32_bf16 v[56:59], v[174:177], v[216:219], v[56:59]
	v_mfma_f32_16x16x32_bf16 v[20:23], v[160:163], v[224:227], v[20:23]
	v_mfma_f32_16x16x32_bf16 v[16:19], v[174:177], v[224:227], v[16:19]
	s_setprio 0
	s_setprio 1
	v_mfma_f32_16x16x32_bf16 v[116:119], v[178:181], v[196:199], v[116:119]
	v_mfma_f32_16x16x32_bf16 v[96:99], v[188:191], v[196:199], v[96:99]
	v_mfma_f32_16x16x32_bf16 v[76:79], v[178:181], v[204:207], v[76:79]
	v_mfma_f32_16x16x32_bf16 v[72:75], v[188:191], v[204:207], v[72:75]
	v_mfma_f32_16x16x32_bf16 v[36:39], v[178:181], v[212:215], v[36:39]
	v_mfma_f32_16x16x32_bf16 v[24:27], v[188:191], v[212:215], v[24:27]
	v_mfma_f32_16x16x32_bf16 v[4:7], v[178:181], v[220:223], v[4:7]
	v_mfma_f32_16x16x32_bf16 v[0:3], v[188:191], v[220:223], v[0:3]
	v_mfma_f32_16x16x32_bf16 v[116:119], v[184:187], v[200:203], v[116:119]
	v_mfma_f32_16x16x32_bf16 v[96:99], v[192:195], v[200:203], v[96:99]
	v_mfma_f32_16x16x32_bf16 v[76:79], v[184:187], v[208:211], v[76:79]
	v_mfma_f32_16x16x32_bf16 v[72:75], v[192:195], v[208:211], v[72:75]
	v_mfma_f32_16x16x32_bf16 v[36:39], v[184:187], v[216:219], v[36:39]
	v_mfma_f32_16x16x32_bf16 v[24:27], v[192:195], v[216:219], v[24:27]
	v_mfma_f32_16x16x32_bf16 v[4:7], v[184:187], v[224:227], v[4:7]
	v_mfma_f32_16x16x32_bf16 v[0:3], v[192:195], v[224:227], v[0:3]
	s_setprio 0
	s_barrier
	s_add_i32 s86, s86, 2
	s_add_u32 s26, s26, 0x100
	s_addc_u32 s27, s27, 0
	s_cmp_gt_u32 s86, 13
	s_cbranch_scc0 .LBB0_773
	s_nop 0
	s_nop 0
	s_nop 0
	s_nop 0
	s_nop 0
	s_nop 0
	s_nop 0
	s_nop 0
	s_nop 0
	s_nop 0
	s_nop 0
	s_nop 0
	s_nop 0
	s_nop 0
	s_nop 0
	s_and_b64 vcc, exec, s[20:21]
	s_cbranch_vccz .LBB0_776
	s_barrier

.LBB0_839:
	ds_read_b128 v[140:143], v151
	ds_read_b128 v[144:147], v151 offset:1024
	ds_read_b128 v[154:157], v151 offset:2048
	ds_read_b128 v[158:161], v151 offset:3072
	ds_read_b128 v[162:165], v152
	ds_read_b128 v[166:169], v152 offset:1024
	ds_read_b128 v[170:173], v152 offset:2048
	ds_read_b128 v[174:177], v152 offset:3072
	s_add_u32 s28, s26, 0xfff80080
	s_addc_u32 s29, s27, -1
	s_cmp_eq_u32 s65, 28
	s_cselect_b32 s31, s49, s29
	s_cselect_b32 s30, s50, s28
	s_cselect_b32 s29, s51, s64
	s_cselect_b32 s28, s52, s53
	v_lshl_add_u64 v[212:213], s[26:27], 0, v[134:135]
	s_add_i32 m0, s35, 0xc000
	ds_read_b128 v[178:181], v153
	ds_read_b128 v[184:187], v153 offset:1024
	ds_read_b128 v[188:191], v153 offset:2048
	ds_read_b128 v[192:195], v153 offset:3072
	ds_read_b128 v[196:199], v153 offset:4096
	ds_read_b128 v[200:203], v153 offset:5120
	ds_read_b128 v[204:207], v153 offset:6144
	ds_read_b128 v[208:211], v153 offset:7168
	global_load_lds_dwordx4 v[212:213], off
	v_lshl_add_u64 v[212:213], s[26:27], 0, v[136:137]
	s_add_i32 m0, s35, 0xe000
	s_nop 0
	global_load_lds_dwordx4 v[212:213], off
	s_nop 0
	s_waitcnt vmcnt(8)
	s_waitcnt lgkmcnt(0)
	s_barrier
	s_setprio 1
	s_waitcnt lgkmcnt(0)
	v_mfma_f32_16x16x32_bf16 v[124:127], v[140:143], v[178:181], v[124:127]
	v_mfma_f32_16x16x32_bf16 v[120:123], v[154:157], v[178:181], v[120:123]
	v_mfma_f32_16x16x32_bf16 v[116:119], v[140:143], v[188:191], v[116:119]
	v_mfma_f32_16x16x32_bf16 v[112:115], v[154:157], v[188:191], v[112:115]
	v_mfma_f32_16x16x32_bf16 v[108:111], v[140:143], v[196:199], v[108:111]
	v_mfma_f32_16x16x32_bf16 v[104:107], v[154:157], v[196:199], v[104:107]
	v_mfma_f32_16x16x32_bf16 v[100:103], v[140:143], v[204:207], v[100:103]
	v_mfma_f32_16x16x32_bf16 v[96:99], v[154:157], v[204:207], v[96:99]
	v_mfma_f32_16x16x32_bf16 v[124:127], v[144:147], v[184:187], v[124:127]
	v_mfma_f32_16x16x32_bf16 v[120:123], v[158:161], v[184:187], v[120:123]
	v_mfma_f32_16x16x32_bf16 v[116:119], v[144:147], v[192:195], v[116:119]
	v_mfma_f32_16x16x32_bf16 v[112:115], v[158:161], v[192:195], v[112:115]
	v_mfma_f32_16x16x32_bf16 v[108:111], v[144:147], v[200:203], v[108:111]
	v_mfma_f32_16x16x32_bf16 v[104:107], v[158:161], v[200:203], v[104:107]
	v_mfma_f32_16x16x32_bf16 v[100:103], v[144:147], v[208:211], v[100:103]
	v_mfma_f32_16x16x32_bf16 v[96:99], v[158:161], v[208:211], v[96:99]
	s_setprio 0
	s_setprio 1
	v_mfma_f32_16x16x32_bf16 v[68:71], v[162:165], v[178:181], v[68:71]
	v_mfma_f32_16x16x32_bf16 v[64:67], v[170:173], v[178:181], v[64:67]
	v_mfma_f32_16x16x32_bf16 v[56:59], v[162:165], v[188:191], v[56:59]
	v_mfma_f32_16x16x32_bf16 v[48:51], v[170:173], v[188:191], v[48:51]
	v_mfma_f32_16x16x32_bf16 v[44:47], v[162:165], v[196:199], v[44:47]
	v_mfma_f32_16x16x32_bf16 v[40:43], v[170:173], v[196:199], v[40:43]
	v_mfma_f32_16x16x32_bf16 v[36:39], v[162:165], v[204:207], v[36:39]
	v_mfma_f32_16x16x32_bf16 v[32:35], v[170:173], v[204:207], v[32:35]
	v_mfma_f32_16x16x32_bf16 v[68:71], v[166:169], v[184:187], v[68:71]
	v_mfma_f32_16x16x32_bf16 v[64:67], v[174:177], v[184:187], v[64:67]
	v_mfma_f32_16x16x32_bf16 v[56:59], v[166:169], v[192:195], v[56:59]
	v_mfma_f32_16x16x32_bf16 v[48:51], v[174:177], v[192:195], v[48:51]
	v_mfma_f32_16x16x32_bf16 v[44:47], v[166:169], v[200:203], v[44:47]
	v_mfma_f32_16x16x32_bf16 v[40:43], v[174:177], v[200:203], v[40:43]
	v_mfma_f32_16x16x32_bf16 v[36:39], v[166:169], v[208:211], v[36:39]
	v_mfma_f32_16x16x32_bf16 v[32:35], v[174:177], v[208:211], v[32:35]
	s_setprio 0
	s_barrier
	s_add_i32 s60, s41, s34
	v_lshl_add_u64 v[212:213], s[28:29], 0, v[128:129]
	s_mov_b32 m0, s60
	ds_read_b128 v[178:181], v153 offset:16384
	ds_read_b128 v[184:187], v153 offset:17408
	ds_read_b128 v[188:191], v153 offset:18432
	ds_read_b128 v[192:195], v153 offset:19456
	ds_read_b128 v[196:199], v153 offset:20480
	ds_read_b128 v[200:203], v153 offset:21504
	ds_read_b128 v[204:207], v153 offset:22528
	ds_read_b128 v[208:211], v153 offset:23552
	global_load_lds_dwordx4 v[212:213], off
	s_add_i32 m0, s60, 0x2000
	s_add_u32 s60, s28, 0x80000
	v_lshl_add_u64 v[214:215], s[28:29], 0, v[130:131]
	s_addc_u32 s61, s29, 0
	s_add_i32 s66, s42, s34
	global_load_lds_dwordx4 v[214:215], off
	v_lshl_add_u64 v[216:217], s[60:61], 0, v[128:129]
	s_mov_b32 m0, s66
	v_lshl_add_u64 v[218:219], s[30:31], 0, v[130:131]
	global_load_lds_dwordx4 v[216:217], off
	v_lshl_add_u64 v[216:217], s[60:61], 0, v[130:131]
	s_add_i32 m0, s66, 0x2000
	s_nop 0
	global_load_lds_dwordx4 v[216:217], off
	v_lshl_add_u64 v[216:217], s[30:31], 0, v[128:129]
	s_mov_b32 m0, s35
	s_nop 0
	global_load_lds_dwordx4 v[216:217], off
	s_mov_b32 m0, s36
	s_nop 0
	global_load_lds_dwordx4 v[218:219], off
	s_nop 0
	s_waitcnt vmcnt(8)
	s_waitcnt lgkmcnt(0)
	s_barrier
	s_setprio 1
	s_waitcnt lgkmcnt(0)
	v_mfma_f32_16x16x32_bf16 v[92:95], v[140:143], v[178:181], v[92:95]
	v_mfma_f32_16x16x32_bf16 v[88:91], v[154:157], v[178:181], v[88:91]
	v_mfma_f32_16x16x32_bf16 v[84:87], v[140:143], v[188:191], v[84:87]
	v_mfma_f32_16x16x32_bf16 v[80:83], v[154:157], v[188:191], v[80:83]
	v_mfma_f32_16x16x32_bf16 v[76:79], v[140:143], v[196:199], v[76:79]
	v_mfma_f32_16x16x32_bf16 v[72:75], v[154:157], v[196:199], v[72:75]
	v_mfma_f32_16x16x32_bf16 v[60:63], v[140:143], v[204:207], v[60:63]
	v_mfma_f32_16x16x32_bf16 v[52:55], v[154:157], v[204:207], v[52:55]
	v_mfma_f32_16x16x32_bf16 v[92:95], v[144:147], v[184:187], v[92:95]
	v_mfma_f32_16x16x32_bf16 v[88:91], v[158:161], v[184:187], v[88:91]
	v_mfma_f32_16x16x32_bf16 v[84:87], v[144:147], v[192:195], v[84:87]
	v_mfma_f32_16x16x32_bf16 v[80:83], v[158:161], v[192:195], v[80:83]
	v_mfma_f32_16x16x32_bf16 v[76:79], v[144:147], v[200:203], v[76:79]
	v_mfma_f32_16x16x32_bf16 v[72:75], v[158:161], v[200:203], v[72:75]
	v_mfma_f32_16x16x32_bf16 v[60:63], v[144:147], v[208:211], v[60:63]
	v_mfma_f32_16x16x32_bf16 v[52:55], v[158:161], v[208:211], v[52:55]
	s_setprio 0
	s_setprio 1
	v_mfma_f32_16x16x32_bf16 v[28:31], v[162:165], v[178:181], v[28:31]
	v_mfma_f32_16x16x32_bf16 v[24:27], v[170:173], v[178:181], v[24:27]
	v_mfma_f32_16x16x32_bf16 v[20:23], v[162:165], v[188:191], v[20:23]
	v_mfma_f32_16x16x32_bf16 v[16:19], v[170:173], v[188:191], v[16:19]
	v_mfma_f32_16x16x32_bf16 v[12:15], v[162:165], v[196:199], v[12:15]
	v_mfma_f32_16x16x32_bf16 v[8:11], v[170:173], v[196:199], v[8:11]
	v_mfma_f32_16x16x32_bf16 v[4:7], v[162:165], v[204:207], v[4:7]
	v_mfma_f32_16x16x32_bf16 v[0:3], v[170:173], v[204:207], v[0:3]
	v_mfma_f32_16x16x32_bf16 v[28:31], v[166:169], v[184:187], v[28:31]
	v_mfma_f32_16x16x32_bf16 v[24:27], v[174:177], v[184:187], v[24:27]
	v_mfma_f32_16x16x32_bf16 v[20:23], v[166:169], v[192:195], v[20:23]
	v_mfma_f32_16x16x32_bf16 v[16:19], v[174:177], v[192:195], v[16:19]
	v_mfma_f32_16x16x32_bf16 v[12:15], v[166:169], v[200:203], v[12:15]
	v_mfma_f32_16x16x32_bf16 v[8:11], v[174:177], v[200:203], v[8:11]
	v_mfma_f32_16x16x32_bf16 v[4:7], v[166:169], v[208:211], v[4:7]
	v_mfma_f32_16x16x32_bf16 v[0:3], v[174:177], v[208:211], v[0:3]
	s_setprio 0
	s_barrier
	s_add_i32 s60, 0, 0x18000
	v_add_u32_e32 v132, s60, v149
	s_add_i32 s61, 0, 0x1c000
	ds_read_b128 v[140:143], v132
	ds_read_b128 v[144:147], v132 offset:1024
	ds_read_b128 v[154:157], v132 offset:2048
	ds_read_b128 v[158:161], v132 offset:3072
	v_add_u32_e32 v132, s61, v149
	ds_read_b128 v[162:165], v132
	ds_read_b128 v[166:169], v132 offset:1024
	ds_read_b128 v[170:173], v132 offset:2048
	ds_read_b128 v[174:177], v132 offset:3072
	s_add_u32 s30, s30, 0x80000
	s_addc_u32 s31, s31, 0
	s_mov_b32 m0, s37
	v_lshl_add_u64 v[220:221], s[30:31], 0, v[128:129]
	ds_read_b128 v[178:181], v153 offset:32768
	ds_read_b128 v[184:187], v153 offset:33792
	ds_read_b128 v[188:191], v153 offset:34816
	ds_read_b128 v[192:195], v153 offset:35840
	ds_read_b128 v[196:199], v153 offset:36864
	ds_read_b128 v[200:203], v153 offset:37888
	ds_read_b128 v[204:207], v153 offset:38912
	ds_read_b128 v[208:211], v153 offset:39936
	global_load_lds_dwordx4 v[220:221], off
	v_lshl_add_u64 v[220:221], s[30:31], 0, v[130:131]
	s_mov_b32 m0, s38
	s_nop 0
	global_load_lds_dwordx4 v[220:221], off
	s_nop 0
	s_waitcnt vmcnt(8)
	s_waitcnt lgkmcnt(0)
	s_barrier
	s_setprio 1
	s_waitcnt lgkmcnt(0)
	v_mfma_f32_16x16x32_bf16 v[124:127], v[140:143], v[178:181], v[124:127]
	v_mfma_f32_16x16x32_bf16 v[120:123], v[154:157], v[178:181], v[120:123]
	v_mfma_f32_16x16x32_bf16 v[116:119], v[140:143], v[188:191], v[116:119]
	v_mfma_f32_16x16x32_bf16 v[112:115], v[154:157], v[188:191], v[112:115]
	v_mfma_f32_16x16x32_bf16 v[108:111], v[140:143], v[196:199], v[108:111]
	v_mfma_f32_16x16x32_bf16 v[104:107], v[154:157], v[196:199], v[104:107]
	v_mfma_f32_16x16x32_bf16 v[100:103], v[140:143], v[204:207], v[100:103]
	v_mfma_f32_16x16x32_bf16 v[96:99], v[154:157], v[204:207], v[96:99]
	v_mfma_f32_16x16x32_bf16 v[124:127], v[144:147], v[184:187], v[124:127]
	v_mfma_f32_16x16x32_bf16 v[120:123], v[158:161], v[184:187], v[120:123]
	v_mfma_f32_16x16x32_bf16 v[116:119], v[144:147], v[192:195], v[116:119]
	v_mfma_f32_16x16x32_bf16 v[112:115], v[158:161], v[192:195], v[112:115]
	v_mfma_f32_16x16x32_bf16 v[108:111], v[144:147], v[200:203], v[108:111]
	v_mfma_f32_16x16x32_bf16 v[104:107], v[158:161], v[200:203], v[104:107]
	v_mfma_f32_16x16x32_bf16 v[100:103], v[144:147], v[208:211], v[100:103]
	v_mfma_f32_16x16x32_bf16 v[96:99], v[158:161], v[208:211], v[96:99]
	s_setprio 0
	s_setprio 1
	v_mfma_f32_16x16x32_bf16 v[68:71], v[162:165], v[178:181], v[68:71]
	v_mfma_f32_16x16x32_bf16 v[64:67], v[170:173], v[178:181], v[64:67]
	v_mfma_f32_16x16x32_bf16 v[56:59], v[162:165], v[188:191], v[56:59]
	v_mfma_f32_16x16x32_bf16 v[48:51], v[170:173], v[188:191], v[48:51]
	v_mfma_f32_16x16x32_bf16 v[44:47], v[162:165], v[196:199], v[44:47]
	v_mfma_f32_16x16x32_bf16 v[40:43], v[170:173], v[196:199], v[40:43]
	v_mfma_f32_16x16x32_bf16 v[36:39], v[162:165], v[204:207], v[36:39]
	v_mfma_f32_16x16x32_bf16 v[32:35], v[170:173], v[204:207], v[32:35]
	v_mfma_f32_16x16x32_bf16 v[68:71], v[166:169], v[184:187], v[68:71]
	v_mfma_f32_16x16x32_bf16 v[64:67], v[174:177], v[184:187], v[64:67]
	v_mfma_f32_16x16x32_bf16 v[56:59], v[166:169], v[192:195], v[56:59]
	v_mfma_f32_16x16x32_bf16 v[48:51], v[174:177], v[192:195], v[48:51]
	v_mfma_f32_16x16x32_bf16 v[44:47], v[166:169], v[200:203], v[44:47]
	v_mfma_f32_16x16x32_bf16 v[40:43], v[174:177], v[200:203], v[40:43]
	v_mfma_f32_16x16x32_bf16 v[36:39], v[166:169], v[208:211], v[36:39]
	v_mfma_f32_16x16x32_bf16 v[32:35], v[174:177], v[208:211], v[32:35]
	s_setprio 0
	s_barrier
	s_add_i32 s30, s60, s34
	v_lshl_add_u64 v[212:213], v[212:213], 0, s[16:17]
	s_mov_b32 m0, s30
	ds_read_b128 v[178:181], v153 offset:49152
	ds_read_b128 v[184:187], v153 offset:50176
	ds_read_b128 v[188:191], v153 offset:51200
	ds_read_b128 v[192:195], v153 offset:52224
	ds_read_b128 v[196:199], v153 offset:53248
	ds_read_b128 v[200:203], v153 offset:54272
	ds_read_b128 v[204:207], v153 offset:55296
	ds_read_b128 v[208:211], v153 offset:56320
	global_load_lds_dwordx4 v[212:213], off
	s_add_i32 m0, s30, 0x2000
	s_add_u32 s28, s28, 0x80080
	v_lshl_add_u64 v[212:213], v[214:215], 0, s[16:17]
	s_addc_u32 s29, s29, 0
	s_add_i32 s30, s61, s34
	global_load_lds_dwordx4 v[212:213], off
	v_lshl_add_u64 v[212:213], s[28:29], 0, v[128:129]
	s_mov_b32 m0, s30
	s_nop 0
	global_load_lds_dwordx4 v[212:213], off
	v_lshl_add_u64 v[212:213], s[28:29], 0, v[130:131]
	s_add_i32 m0, s30, 0x2000
	s_nop 0
	global_load_lds_dwordx4 v[212:213], off
	v_lshl_add_u64 v[212:213], v[216:217], 0, s[16:17]
	s_mov_b32 m0, s3
	s_nop 0
	global_load_lds_dwordx4 v[212:213], off
	v_lshl_add_u64 v[212:213], v[218:219], 0, s[16:17]
	s_mov_b32 m0, s40
	s_nop 0
	global_load_lds_dwordx4 v[212:213], off
	s_waitcnt vmcnt(8)
	s_waitcnt lgkmcnt(0)
	s_barrier
	s_setprio 1
	s_waitcnt lgkmcnt(0)
	v_mfma_f32_16x16x32_bf16 v[92:95], v[140:143], v[178:181], v[92:95]
	v_mfma_f32_16x16x32_bf16 v[88:91], v[154:157], v[178:181], v[88:91]
	v_mfma_f32_16x16x32_bf16 v[84:87], v[140:143], v[188:191], v[84:87]
	v_mfma_f32_16x16x32_bf16 v[80:83], v[154:157], v[188:191], v[80:83]
	v_mfma_f32_16x16x32_bf16 v[76:79], v[140:143], v[196:199], v[76:79]
	v_mfma_f32_16x16x32_bf16 v[72:75], v[154:157], v[196:199], v[72:75]
	v_mfma_f32_16x16x32_bf16 v[60:63], v[140:143], v[204:207], v[60:63]
	v_mfma_f32_16x16x32_bf16 v[52:55], v[154:157], v[204:207], v[52:55]
	v_mfma_f32_16x16x32_bf16 v[92:95], v[144:147], v[184:187], v[92:95]
	v_mfma_f32_16x16x32_bf16 v[88:91], v[158:161], v[184:187], v[88:91]
	v_mfma_f32_16x16x32_bf16 v[84:87], v[144:147], v[192:195], v[84:87]
	v_mfma_f32_16x16x32_bf16 v[80:83], v[158:161], v[192:195], v[80:83]
	v_mfma_f32_16x16x32_bf16 v[76:79], v[144:147], v[200:203], v[76:79]
	v_mfma_f32_16x16x32_bf16 v[72:75], v[158:161], v[200:203], v[72:75]
	v_mfma_f32_16x16x32_bf16 v[60:63], v[144:147], v[208:211], v[60:63]
	v_mfma_f32_16x16x32_bf16 v[52:55], v[158:161], v[208:211], v[52:55]
	s_setprio 0
	s_setprio 1
	v_mfma_f32_16x16x32_bf16 v[28:31], v[162:165], v[178:181], v[28:31]
	v_mfma_f32_16x16x32_bf16 v[24:27], v[170:173], v[178:181], v[24:27]
	v_mfma_f32_16x16x32_bf16 v[20:23], v[162:165], v[188:191], v[20:23]
	v_mfma_f32_16x16x32_bf16 v[16:19], v[170:173], v[188:191], v[16:19]
	v_mfma_f32_16x16x32_bf16 v[12:15], v[162:165], v[196:199], v[12:15]
	v_mfma_f32_16x16x32_bf16 v[8:11], v[170:173], v[196:199], v[8:11]
	v_mfma_f32_16x16x32_bf16 v[4:7], v[162:165], v[204:207], v[4:7]
	v_mfma_f32_16x16x32_bf16 v[0:3], v[170:173], v[204:207], v[0:3]
	v_mfma_f32_16x16x32_bf16 v[28:31], v[166:169], v[184:187], v[28:31]
	v_mfma_f32_16x16x32_bf16 v[24:27], v[174:177], v[184:187], v[24:27]
	v_mfma_f32_16x16x32_bf16 v[20:23], v[166:169], v[192:195], v[20:23]
	v_mfma_f32_16x16x32_bf16 v[16:19], v[174:177], v[192:195], v[16:19]
	v_mfma_f32_16x16x32_bf16 v[12:15], v[166:169], v[200:203], v[12:15]
	v_mfma_f32_16x16x32_bf16 v[8:11], v[174:177], v[200:203], v[8:11]
	v_mfma_f32_16x16x32_bf16 v[4:7], v[166:169], v[208:211], v[4:7]
	v_mfma_f32_16x16x32_bf16 v[0:3], v[174:177], v[208:211], v[0:3]
	s_setprio 0
	s_barrier
	s_add_i32 s65, s65, 2
	s_add_u32 s26, s26, 0x100
	s_addc_u32 s27, s27, 0
	s_add_u32 s53, s53, 0x100
	s_addc_u32 s64, s64, 0
	s_cmp_gt_u32 s65, 29
	s_cbranch_scc0 .LBB0_839
	s_nop 0
	s_nop 0
	s_nop 0
	s_nop 0
	s_nop 0
	s_nop 0
	s_nop 0
	s_nop 0
	s_nop 0
	s_nop 0
	s_nop 0
	s_nop 0
	s_nop 0
	s_and_b64 vcc, exec, s[18:19]
	s_cbranch_vccz .LBB0_842
	s_barrier
